# attention: next unit's Q fragment loads issued right after the last QK^T MFMA instead of at the end of the unit
# baseline (speedup 1.0000x reference)
; #define LAS __attribute__((address_space(3)))
; #define LAS __attribute__((address_space(3)))
; #define ATT_LDK(t) do { kfr[t][0] = *(const LAS bf16x8*)(kp0 + (t) * 16 * 72); kfr[t][1] = *(const LAS bf16x8*)(kp0 + (t) * 16 * 72 + 32); } while (0)
; __device__ __forceinline__ void attn_phase(LAS unsigned char* lds, const bf16* PROJ, bf16* CONCAT, const float* sinks) {
;     ...
;         const int u = ATT_UNIT(ul);
;         const int kh = u & 1, n = (u >> 1) & 63, b = u >> 7;
;         const int g = wave >> 1, h = kh * 4 + g;
;         const size_t qrow0 = (size_t)b * SEQ + n * 128 + (wave & 1) * 64 + fr;
; #pragma unroll
;         for (int i = 0; i < 4; ++i) { const int kj = lane + 64 * i;
;             *(LAS v4u*)(Ks + kj * 72 + wave * 8) = kv[i];
;             *(LAS v4u*)(Vs + kj * 72 + wave * 8) = vv[i]; }
;         __syncthreads();
;         if (ul + (int)gridDim.x < NB * 64 * 2) ATT_LOAD_KV(ATT_UNIT(ul + (int)gridDim.x));
;         const float sink = sinks[h];
;         const int firstblk = (n == 0);
; #pragma unroll
;         for (int p = 0; p < 2; ++p) {
;             const int q16a = (wave & 1) * 4 + 2 * p, kt0 = q16a;
;             f32x4 st[2][10];
;             bf16x8 kfr[10][2];
;             const LAS bf16* kp0 = Ks + (16 * kt0 + fr) * 72 + 8 * fq;
;     ...
;             ATT_LDK(0);
; #pragma unroll
;             for (int t = 0; t < 10; ++t) {
;                 if (t + 1 < 10) ATT_LDK(t + 1);
; #pragma unroll
;                 for (int x = 0; x < 2; ++x) {
;                     if (x + 8 - t == 9 || x + 8 - t == -1) { st[x][t] = (f32x4){-1e30f, -1e30f, -1e30f, -1e30f}; continue; }
;                     f32x4 acc = (f32x4){0.f, 0.f, 0.f, 0.f};
;                     acc = __builtin_amdgcn_mfma_f32_16x16x32_bf16(kfr[t][0], qf[2 * p + x][0], acc, 0, 0, 0);
;                     acc = __builtin_amdgcn_mfma_f32_16x16x32_bf16(kfr[t][1], qf[2 * p + x][1], acc, 0, 0, 0);
;                     st[x][t] = acc;
;                 }
;             }
.LBB0_278:
	s_lshl_b32 s37, s52, 2
	s_and_b32 s51, s37, 4
	v_add_u32_e32 v68, s51, v133
	v_ashrrev_i32_e32 v69, 31, v68
	v_lshl_add_u64 v[70:71], v[68:69], 2, s[0:1]
	global_load_dword v144, v[70:71], off
	v_lshlrev_b32_e32 v68, 6, v68
	v_ashrrev_i32_e32 v69, 31, v68
	v_lshl_add_u64 v[146:147], v[68:69], 1, v[138:139]
	ds_read_b128 v[68:71], v151
	ds_read_b128 v[72:75], v151 offset:64
	ds_read_b128 v[76:79], v151 offset:2304
	ds_read_b128 v[80:83], v151 offset:2368
	s_waitcnt vmcnt(1) lgkmcnt(3)
	v_mfma_f32_16x16x32_bf16 v[68:71], v[68:71], v[32:35], 0
	s_ashr_i32 s36, s52, 7
	s_bfe_u32 s50, s52, 0x60001
	s_ashr_i32 s37, s36, 31
	s_waitcnt lgkmcnt(2)
	v_mfma_f32_16x16x32_bf16 v[158:161], v[72:75], v[28:31], v[68:71]
	s_nop 2
	ds_read_b128 v[68:71], v151 offset:4608
	ds_read_b128 v[84:87], v151 offset:4672
	s_lshl_b32 s52, s50, 7
	s_lshl_b64 s[36:37], s[36:37], 13
	s_waitcnt lgkmcnt(3)
	v_mfma_f32_16x16x32_bf16 v[72:75], v[76:79], v[32:35], 0
	s_or_b32 s36, s36, s52
	s_cmp_lg_u32 s50, 0
	s_cselect_b64 s[60:61], -1, 0
	s_waitcnt lgkmcnt(2)
	v_mfma_f32_16x16x32_bf16 v[104:107], v[80:83], v[28:31], v[72:75]
	s_and_b64 s[50:51], s[60:61], s[38:39]
	s_and_b64 s[52:53], s[60:61], s[40:41]
	v_cndmask_b32_e64 v143, v197, v158, s[50:51]
	v_mfma_f32_16x16x32_bf16 v[72:75], v[76:79], v[40:43], 0
	v_cndmask_b32_e64 v157, v197, v159, s[52:53]
	s_and_b64 s[54:55], s[60:61], s[42:43]
	s_and_b64 s[56:57], s[60:61], s[44:45]
	v_mfma_f32_16x16x32_bf16 v[72:75], v[80:83], v[36:39], v[72:75]
	ds_read_b128 v[80:83], v151 offset:6912
	ds_read_b128 v[88:91], v151 offset:6976
	v_max3_f32 v145, v143, s78, v157
	v_cndmask_b32_e64 v158, v197, v160, s[54:55]
	s_waitcnt lgkmcnt(3)
	v_mfma_f32_16x16x32_bf16 v[76:79], v[68:71], v[32:35], 0
	v_cndmask_b32_e64 v159, v197, v161, s[56:57]
	v_max3_f32 v145, v145, v158, v159
	v_cndmask_b32_e64 v104, v197, v104, s[60:61]
	v_mfma_f32_16x16x32_bf16 v[68:71], v[68:71], v[40:43], 0
	v_cndmask_b32_e64 v105, v197, v105, s[60:61]
	v_max3_f32 v145, v145, v104, v105
	v_cndmask_b32_e64 v106, v197, v106, s[60:61]
	s_waitcnt lgkmcnt(2)
	v_mfma_f32_16x16x32_bf16 v[108:111], v[84:87], v[28:31], v[76:79]
	v_cndmask_b32_e64 v107, v197, v107, s[60:61]
	v_max3_f32 v145, v145, v106, v107
	s_or_b64 s[58:59], s[60:61], s[46:47]
	v_mfma_f32_16x16x32_bf16 v[76:79], v[84:87], v[36:39], v[68:71]
	s_nop 2
	ds_read_b128 v[68:71], v151 offset:9216
	ds_read_b128 v[84:87], v151 offset:9280
	v_cndmask_b32_e64 v108, v197, v108, s[60:61]
	v_cndmask_b32_e64 v109, v197, v109, s[60:61]
	s_waitcnt lgkmcnt(3)
	v_mfma_f32_16x16x32_bf16 v[92:95], v[80:83], v[32:35], 0
	v_max3_f32 v145, v145, v108, v109
	v_cndmask_b32_e64 v110, v197, v110, s[60:61]
	v_cndmask_b32_e64 v111, v197, v111, s[60:61]
	v_mfma_f32_16x16x32_bf16 v[80:83], v[80:83], v[40:43], 0
	v_max3_f32 v145, v145, v110, v111
	v_cndmask_b32_e64 v74, v197, v74, s[54:55]
	v_cndmask_b32_e64 v75, v197, v75, s[56:57]
	s_waitcnt lgkmcnt(2)
	v_mfma_f32_16x16x32_bf16 v[112:115], v[88:91], v[28:31], v[92:95]
	v_cndmask_b32_e64 v76, v197, v76, s[60:61]
	v_cndmask_b32_e64 v77, v197, v77, s[60:61]
	v_cndmask_b32_e64 v78, v197, v78, s[60:61]
	v_mfma_f32_16x16x32_bf16 v[80:83], v[88:91], v[36:39], v[80:83]
	ds_read_b128 v[88:91], v151 offset:11520
	ds_read_b128 v[92:95], v151 offset:11584
	s_nop 1
	v_cndmask_b32_e64 v160, v197, v112, s[60:61]
	v_cndmask_b32_e64 v161, v197, v113, s[60:61]
	s_waitcnt lgkmcnt(3)
	v_mfma_f32_16x16x32_bf16 v[96:99], v[68:71], v[32:35], 0
	v_max3_f32 v112, v145, v160, v161
	v_cndmask_b32_e64 v114, v197, v114, s[60:61]
	v_cndmask_b32_e64 v115, v197, v115, s[60:61]
	v_mfma_f32_16x16x32_bf16 v[68:71], v[68:71], v[40:43], 0
	v_max3_f32 v112, v112, v114, v115
	v_cndmask_b32_e64 v79, v197, v79, s[60:61]
	v_cndmask_b32_e64 v80, v197, v80, s[60:61]
	s_waitcnt lgkmcnt(2)
	v_mfma_f32_16x16x32_bf16 v[116:119], v[84:87], v[28:31], v[96:99]
	v_cndmask_b32_e64 v81, v197, v81, s[60:61]
	v_cndmask_b32_e64 v82, v197, v82, s[60:61]
	v_cndmask_b32_e64 v83, v197, v83, s[60:61]
	v_mfma_f32_16x16x32_bf16 v[84:87], v[84:87], v[36:39], v[68:71]
	s_nop 2
	ds_read_b128 v[68:71], v151 offset:13824
	ds_read_b128 v[96:99], v151 offset:13888
	v_cndmask_b32_e64 v116, v197, v116, s[58:59]
	v_cndmask_b32_e64 v117, v197, v117, s[58:59]
	s_waitcnt lgkmcnt(3)
	v_mfma_f32_16x16x32_bf16 v[100:103], v[88:91], v[32:35], 0
	v_max3_f32 v112, v112, v116, v117
	v_cndmask_b32_e64 v118, v197, v118, s[58:59]
	v_cndmask_b32_e64 v190, v197, v119, s[58:59]
	v_mfma_f32_16x16x32_bf16 v[88:91], v[88:91], v[40:43], 0
	v_max3_f32 v112, v112, v118, v190
	v_cndmask_b32_e64 v84, v197, v84, s[58:59]
	s_waitcnt lgkmcnt(2)
	v_mfma_f32_16x16x32_bf16 v[120:123], v[92:95], v[28:31], v[100:103]
	s_nop 2
	ds_read_b128 v[100:103], v151 offset:16128
	ds_read_b128 v[174:177], v151 offset:16192
	s_nop 2
	v_cndmask_b32_e64 v191, v197, v120, s[58:59]
	v_mfma_f32_16x16x32_bf16 v[88:91], v[92:95], v[36:39], v[88:91]
	v_cndmask_b32_e64 v199, v197, v121, s[58:59]
	v_max3_f32 v112, v112, v191, v199
	v_cndmask_b32_e64 v200, v197, v122, s[58:59]
	s_waitcnt lgkmcnt(3)
	v_mfma_f32_16x16x32_bf16 v[92:95], v[68:71], v[32:35], 0
	v_cndmask_b32_e64 v201, v197, v123, s[58:59]
	v_max3_f32 v112, v112, v200, v201
	v_mfma_f32_16x16x32_bf16 v[68:71], v[68:71], v[40:43], 0
	s_waitcnt lgkmcnt(2)
	v_mfma_f32_16x16x32_bf16 v[124:127], v[96:99], v[28:31], v[92:95]
	v_mfma_f32_16x16x32_bf16 v[92:95], v[96:99], v[36:39], v[68:71]
	s_nop 4
	ds_read_b128 v[68:71], v151 offset:18432
	ds_read_b128 v[178:181], v151 offset:18496
	v_cndmask_b32_e64 v202, v197, v124, s[58:59]
	v_cndmask_b32_e64 v203, v197, v125, s[58:59]
	s_waitcnt lgkmcnt(3)
; __device__ __forceinline__ void attn_phase(LAS unsigned char* lds, const bf16* PROJ, bf16* CONCAT, const float* sinks) {
;     ...
; #pragma unroll
;             for (int t = 0; t < 10; ++t) {
;                 if (t + 1 < 10) ATT_LDK(t + 1);
; #pragma unroll
;                 for (int x = 0; x < 2; ++x) {
;                     if (x + 8 - t == 9 || x + 8 - t == -1) { st[x][t] = (f32x4){-1e30f, -1e30f, -1e30f, -1e30f}; continue; }
;                     f32x4 acc = (f32x4){0.f, 0.f, 0.f, 0.f};
;                     acc = __builtin_amdgcn_mfma_f32_16x16x32_bf16(kfr[t][0], qf[2 * p + x][0], acc, 0, 0, 0);
;                     acc = __builtin_amdgcn_mfma_f32_16x16x32_bf16(kfr[t][1], qf[2 * p + x][1], acc, 0, 0, 0);
;                     st[x][t] = acc;
;                 }
;             }
;     ...
;             float inv[2];
; #pragma unroll
;             for (int x = 0; x < 2; ++x) {
;                 float mx = -1e30f;
; #pragma unroll
;                 for (int t = 0; t < 10; ++t) {
;                     const int D = x + 8 - t;
;                     if (D == 9 || D == -1) continue;
;                     const bool tile_off = firstblk && (kt0 + t < 8);
; #pragma unroll
;                     for (int r = 0; r < 4; ++r) { const int dl = fr - 4 * fq - r;
;                         bool valid = !tile_off;
;                         if (D == 8) valid = valid && (dl < 0);
;                         if (D == 0) valid = valid && (dl >= 0);
;                         const float sv = valid ? st[x][t][r] : -1e30f; st[x][t][r] = sv; mx = fmaxf(mx, sv); }
;                 }
;                 mx = fmaxf(mx, __shfl_xor(mx, 16)); mx = fmaxf(mx, __shfl_xor(mx, 32)); mx = fmaxf(mx, sink);
;                 const float mb = mx * LOG2E;
;                 float lsum = 0.f;
; #pragma unroll
;                 for (int t = 0; t < 10; ++t) {
;                     const int D = x + 8 - t;
;                     if (D == 9 || D == -1) { st[x][t] = (f32x4){0.f, 0.f, 0.f, 0.f}; continue; }
; #pragma unroll
;                     for (int r = 0; r < 4; ++r) { const float pe = __builtin_amdgcn_exp2f(st[x][t][r] * LOG2E - mb); st[x][t][r] = pe; lsum += pe; }
;                 }
;                 lsum += __shfl_xor(lsum, 16); lsum += __shfl_xor(lsum, 32); lsum += __builtin_amdgcn_exp2f(sink * LOG2E - mb);
;                 inv[x] = 1.0f / lsum;
	v_mfma_f32_16x16x32_bf16 v[96:99], v[100:103], v[32:35], 0
	v_max3_f32 v112, v112, v202, v203
	v_cndmask_b32_e64 v208, v197, v126, s[58:59]
	v_cndmask_b32_e64 v209, v197, v127, s[58:59]
	s_waitcnt lgkmcnt(1)
	v_mfma_f32_16x16x32_bf16 v[186:189], v[68:71], v[32:35], 0
	v_max3_f32 v112, v112, v208, v209
	v_mfma_f32_16x16x32_bf16 v[182:185], v[174:177], v[28:31], v[96:99]
	s_waitcnt lgkmcnt(0)
	v_mfma_f32_16x16x32_bf16 v[186:189], v[178:181], v[28:31], v[186:189]
	v_mfma_f32_16x16x32_bf16 v[96:99], v[100:103], v[40:43], 0
	s_nop 4
	v_cndmask_b32_e64 v182, v197, v182, s[58:59]
	v_cndmask_b32_e64 v183, v197, v183, s[58:59]
	v_max3_f32 v112, v112, v182, v183
	v_cndmask_b32_e64 v184, v197, v184, s[58:59]
	v_cndmask_b32_e64 v185, v197, v185, s[58:59]
	v_max3_f32 v112, v112, v184, v185
	v_cndmask_b32_e64 v186, v186, v197, s[38:39]
	v_cndmask_b32_e64 v187, v197, v187, s[48:49]
	v_max3_f32 v112, v112, v186, v187
	v_cndmask_b32_e64 v188, v188, v197, s[42:43]
	v_cndmask_b32_e64 v189, v189, v197, s[44:45]
	v_max3_f32 v112, v112, v188, v189
	ds_bpermute_b32 v113, v135, v112
	v_mfma_f32_16x16x32_bf16 v[96:99], v[174:177], v[36:39], v[96:99]
	ds_read_b128 v[100:103], v151 offset:20736
	ds_read_b128 v[174:177], v151 offset:20800
	s_waitcnt lgkmcnt(2)
	v_max_f32_e32 v113, v113, v113
	v_max_f32_e32 v112, v112, v113
	ds_bpermute_b32 v113, v148, v112
	s_waitcnt lgkmcnt(2)
	v_mfma_f32_16x16x32_bf16 v[100:103], v[100:103], v[40:43], 0
	v_cndmask_b32_e64 v210, v197, v99, s[58:59]
	s_waitcnt vmcnt(0) lgkmcnt(0)
	v_max3_f32 v145, v112, v113, v144
	v_pk_mul_f32 v[112:113], v[144:145], s[26:27] op_sel_hi:[1,0]
	v_mfma_f32_16x16x32_bf16 v[68:71], v[68:71], v[40:43], 0
	v_fma_f32 v119, v143, s26, -v113
	v_fma_f32 v120, v157, s26, -v113
	v_fma_f32 v104, v104, s26, -v113
	v_mfma_f32_16x16x32_bf16 v[100:103], v[174:177], v[36:39], v[100:103]
	v_exp_f32_e32 v174, v119
	v_exp_f32_e32 v175, v120
	v_fma_f32 v120, v158, s26, -v113
	v_exp_f32_e32 v176, v120
	v_fma_f32 v120, v159, s26, -v113
	v_exp_f32_e32 v177, v120
	v_mfma_f32_16x16x32_bf16 v[68:71], v[178:181], v[36:39], v[68:71]
	v_add_f32_e32 v119, 0, v174
	v_exp_f32_e32 v178, v104
	v_fma_f32 v105, v105, s26, -v113
	v_add_f32_e32 v119, v175, v119
	v_exp_f32_e32 v179, v105
	v_fma_f32 v105, v106, s26, -v113
	v_add_f32_e32 v119, v176, v119
	v_exp_f32_e32 v180, v105
	v_fma_f32 v105, v107, s26, -v113
	v_add_f32_e32 v119, v177, v119
	v_exp_f32_e32 v181, v105
	v_fma_f32 v105, v108, s26, -v113
	v_add_f32_e32 v104, v178, v119
	v_exp_f32_e32 v127, v105
	v_fma_f32 v105, v109, s26, -v113
	v_add_f32_e32 v104, v179, v104
	v_exp_f32_e32 v143, v105
	v_fma_f32 v105, v110, s26, -v113
	v_add_f32_e32 v104, v180, v104
	v_exp_f32_e32 v145, v105
	v_fma_f32 v105, v111, s26, -v113
	v_add_f32_e32 v104, v181, v104
	v_exp_f32_e32 v157, v105
	v_fma_f32 v105, v160, s26, -v113
	v_add_f32_e32 v104, v127, v104
	v_exp_f32_e32 v158, v105
	v_fma_f32 v105, v161, s26, -v113
	v_add_f32_e32 v104, v143, v104
	v_exp_f32_e32 v159, v105
	v_fma_f32 v105, v114, s26, -v113
	v_add_f32_e32 v104, v145, v104
	v_exp_f32_e32 v160, v105
	v_fma_f32 v105, v115, s26, -v113
	v_add_f32_e32 v104, v157, v104
	v_exp_f32_e32 v161, v105
	v_fma_f32 v105, v116, s26, -v113
	v_add_f32_e32 v104, v158, v104
	v_exp_f32_e32 v119, v105
	v_fma_f32 v105, v117, s26, -v113
	v_add_f32_e32 v104, v159, v104
	v_exp_f32_e32 v120, v105
	v_fma_f32 v105, v118, s26, -v113
	v_add_f32_e32 v104, v160, v104
	v_exp_f32_e32 v121, v105
	v_fma_f32 v105, v190, s26, -v113
	v_add_f32_e32 v104, v161, v104
	v_exp_f32_e32 v122, v105
	v_fma_f32 v105, v191, s26, -v113
	v_add_f32_e32 v104, v119, v104
	v_exp_f32_e32 v123, v105
	v_fma_f32 v105, v199, s26, -v113
	v_add_f32_e32 v104, v120, v104
	v_exp_f32_e32 v124, v105
	v_fma_f32 v105, v200, s26, -v113
	v_add_f32_e32 v104, v121, v104
	v_exp_f32_e32 v125, v105
	v_fma_f32 v105, v201, s26, -v113
	v_add_f32_e32 v104, v122, v104
	v_exp_f32_e32 v126, v105
	v_fma_f32 v105, v202, s26, -v113
	v_add_f32_e32 v104, v123, v104
	v_exp_f32_e32 v109, v105
	v_fma_f32 v105, v203, s26, -v113
	v_add_f32_e32 v104, v124, v104
	v_exp_f32_e32 v110, v105
	v_fma_f32 v105, v208, s26, -v113
	v_add_f32_e32 v104, v125, v104
	v_exp_f32_e32 v111, v105
	v_fma_f32 v105, v209, s26, -v113
	v_add_f32_e32 v104, v126, v104
	v_exp_f32_e32 v114, v105
	v_fma_f32 v105, v182, s26, -v113
	v_add_f32_e32 v104, v109, v104
	v_exp_f32_e32 v115, v105
	v_fma_f32 v105, v183, s26, -v113
	v_add_f32_e32 v104, v110, v104
	v_exp_f32_e32 v116, v105
	v_fma_f32 v105, v184, s26, -v113
	v_add_f32_e32 v104, v111, v104
	v_exp_f32_e32 v117, v105
	v_fma_f32 v105, v185, s26, -v113
	v_add_f32_e32 v104, v114, v104
	v_exp_f32_e32 v118, v105
	v_fma_f32 v105, v186, s26, -v113
	v_add_f32_e32 v104, v115, v104
	v_exp_f32_e32 v105, v105
	v_fma_f32 v106, v187, s26, -v113
	v_add_f32_e32 v104, v116, v104
	v_exp_f32_e32 v106, v106
	v_fma_f32 v107, v188, s26, -v113
	v_add_f32_e32 v104, v117, v104
	v_exp_f32_e32 v107, v107
	v_fma_f32 v108, v189, s26, -v113
	v_add_f32_e32 v104, v118, v104
	v_exp_f32_e32 v108, v108
	v_add_f32_e32 v104, v105, v104
	v_add_f32_e32 v104, v106, v104
	v_add_f32_e32 v104, v107, v104
	v_add_f32_e32 v104, v108, v104
	ds_bpermute_b32 v182, v135, v104
	v_sub_f32_e32 v113, v112, v113
	v_exp_f32_e32 v113, v113
	v_cndmask_b32_e64 v186, v197, v86, s[58:59]
	v_cndmask_b32_e64 v187, v197, v87, s[58:59]
	s_waitcnt lgkmcnt(0)
	v_add_f32_e32 v104, v104, v182
	ds_bpermute_b32 v182, v148, v104
	v_cndmask_b32_e64 v188, v197, v88, s[58:59]
	v_cndmask_b32_e64 v189, v197, v89, s[58:59]
	v_cndmask_b32_e64 v190, v197, v90, s[58:59]
	v_cndmask_b32_e64 v191, v197, v91, s[58:59]
	s_waitcnt lgkmcnt(0)
; __device__ __forceinline__ void attn_phase(LAS unsigned char* lds, const bf16* PROJ, bf16* CONCAT, const float* sinks) {
;     ...
;             float inv[2];
; #pragma unroll
;             for (int x = 0; x < 2; ++x) {
;                 float mx = -1e30f;
; #pragma unroll
;                 for (int t = 0; t < 10; ++t) {
;                     const int D = x + 8 - t;
;                     if (D == 9 || D == -1) continue;
;                     const bool tile_off = firstblk && (kt0 + t < 8);
; #pragma unroll
;                     for (int r = 0; r < 4; ++r) { const int dl = fr - 4 * fq - r;
;                         bool valid = !tile_off;
;                         if (D == 8) valid = valid && (dl < 0);
;                         if (D == 0) valid = valid && (dl >= 0);
;                         const float sv = valid ? st[x][t][r] : -1e30f; st[x][t][r] = sv; mx = fmaxf(mx, sv); }
;                 }
;                 mx = fmaxf(mx, __shfl_xor(mx, 16)); mx = fmaxf(mx, __shfl_xor(mx, 32)); mx = fmaxf(mx, sink);
;                 const float mb = mx * LOG2E;
;                 float lsum = 0.f;
; #pragma unroll
;                 for (int t = 0; t < 10; ++t) {
;                     const int D = x + 8 - t;
;                     if (D == 9 || D == -1) { st[x][t] = (f32x4){0.f, 0.f, 0.f, 0.f}; continue; }
; #pragma unroll
;                     for (int r = 0; r < 4; ++r) { const float pe = __builtin_amdgcn_exp2f(st[x][t][r] * LOG2E - mb); st[x][t][r] = pe; lsum += pe; }
;                 }
;                 lsum += __shfl_xor(lsum, 16); lsum += __shfl_xor(lsum, 32); lsum += __builtin_amdgcn_exp2f(sink * LOG2E - mb);
;                 inv[x] = 1.0f / lsum;
	v_add_f32_e32 v104, v104, v182
	v_add_f32_e32 v104, v113, v104
	v_div_scale_f32 v113, s[70:71], v104, v104, 1.0
	v_rcp_f32_e32 v182, v113
	v_cndmask_b32_e64 v199, v197, v92, s[58:59]
	v_cndmask_b32_e64 v200, v197, v93, s[58:59]
	v_cndmask_b32_e64 v201, v197, v94, s[58:59]
	v_fma_f32 v183, -v113, v182, 1.0
	v_fmac_f32_e32 v182, v183, v182
	v_div_scale_f32 v183, vcc, 1.0, v104, 1.0
	v_mul_f32_e32 v184, v183, v182
	v_fma_f32 v185, -v113, v184, v183
	v_fmac_f32_e32 v184, v185, v182
	v_fma_f32 v113, -v113, v184, v183
	v_div_fmas_f32 v113, v113, v182, v184
	v_div_fixup_f32 v104, v113, v104, 1.0
	v_cndmask_b32_e64 v113, v197, v72, s[50:51]
	v_cndmask_b32_e64 v184, v197, v73, s[52:53]
	v_max3_f32 v72, v113, s78, v184
	v_max3_f32 v72, v72, v74, v75
	v_max3_f32 v72, v72, v76, v77
	v_max3_f32 v72, v72, v78, v79
	v_max3_f32 v72, v72, v80, v81
	v_max3_f32 v72, v72, v82, v83
	v_cndmask_b32_e64 v185, v197, v85, s[58:59]
	v_max3_f32 v72, v72, v84, v185
	v_max3_f32 v72, v72, v186, v187
	v_max3_f32 v72, v72, v188, v189
	v_max3_f32 v72, v72, v190, v191
	v_max3_f32 v72, v72, v199, v200
	v_cndmask_b32_e64 v202, v197, v95, s[58:59]
	v_max3_f32 v72, v72, v201, v202
	v_cndmask_b32_e64 v203, v197, v96, s[58:59]
	v_cndmask_b32_e64 v208, v197, v97, s[58:59]
	v_max3_f32 v72, v72, v203, v208
	v_cndmask_b32_e64 v209, v197, v98, s[58:59]
	v_max3_f32 v72, v72, v209, v210
	v_max3_f32 v72, v72, v68, v69
	v_max3_f32 v73, v72, v70, v71
	v_cndmask_b32_e64 v211, v100, v197, s[38:39]
	v_cndmask_b32_e64 v212, v197, v101, s[48:49]
	v_cndmask_b32_e64 v72, v102, v197, s[42:43]
	v_cndmask_b32_e64 v213, v103, v197, s[44:45]
	v_max3_f32 v73, v73, v211, v212
	v_max3_f32 v73, v73, v72, v213
	ds_bpermute_b32 v85, v135, v73
	s_waitcnt lgkmcnt(0)
	v_max_f32_e32 v85, v85, v85
	v_max_f32_e32 v73, v73, v85
	ds_bpermute_b32 v85, v148, v73
	s_waitcnt lgkmcnt(0)
	v_max3_f32 v73, v73, v85, v144
	v_pk_mul_f32 v[182:183], v[72:73], s[26:27] op_sel_hi:[1,0]
	s_nop 0
	v_fma_f32 v72, v113, s26, -v183
	v_exp_f32_e32 v101, v72
	v_fma_f32 v73, v184, s26, -v183
	v_exp_f32_e32 v102, v73
	v_fma_f32 v73, v74, s26, -v183
	v_exp_f32_e32 v103, v73
	v_fma_f32 v73, v75, s26, -v183
	v_exp_f32_e32 v113, v73
	v_fma_f32 v73, v76, s26, -v183
	v_add_f32_e32 v72, 0, v101
	v_exp_f32_e32 v93, v73
	v_fma_f32 v73, v77, s26, -v183
	v_add_f32_e32 v72, v102, v72
	v_exp_f32_e32 v94, v73
	v_fma_f32 v73, v78, s26, -v183
	v_add_f32_e32 v72, v103, v72
	v_exp_f32_e32 v95, v73
	v_fma_f32 v73, v79, s26, -v183
	v_add_f32_e32 v72, v113, v72
	v_exp_f32_e32 v96, v73
	v_fma_f32 v73, v80, s26, -v183
	v_add_f32_e32 v72, v93, v72
	v_exp_f32_e32 v97, v73
	v_fma_f32 v73, v81, s26, -v183
	v_add_f32_e32 v72, v94, v72
	v_exp_f32_e32 v98, v73
	v_fma_f32 v73, v82, s26, -v183
	v_add_f32_e32 v72, v95, v72
	v_exp_f32_e32 v99, v73
	v_fma_f32 v73, v83, s26, -v183
	v_add_f32_e32 v72, v96, v72
	v_exp_f32_e32 v100, v73
	v_fma_f32 v73, v84, s26, -v183
	v_add_f32_e32 v72, v97, v72
	v_exp_f32_e32 v85, v73
	v_fma_f32 v73, v185, s26, -v183
	v_add_f32_e32 v72, v98, v72
	v_exp_f32_e32 v86, v73
	v_fma_f32 v73, v186, s26, -v183
	v_add_f32_e32 v72, v99, v72
	v_exp_f32_e32 v87, v73
	v_fma_f32 v73, v187, s26, -v183
	v_add_f32_e32 v72, v100, v72
	v_exp_f32_e32 v88, v73
	v_fma_f32 v73, v188, s26, -v183
	v_add_f32_e32 v72, v85, v72
	v_exp_f32_e32 v89, v73
	v_fma_f32 v73, v189, s26, -v183
	v_add_f32_e32 v72, v86, v72
	v_exp_f32_e32 v90, v73
	v_fma_f32 v73, v190, s26, -v183
	v_add_f32_e32 v72, v87, v72
	v_exp_f32_e32 v91, v73
	v_fma_f32 v73, v191, s26, -v183
	v_add_f32_e32 v72, v88, v72
	v_exp_f32_e32 v92, v73
	v_fma_f32 v73, v199, s26, -v183
	v_add_f32_e32 v72, v89, v72
	v_exp_f32_e32 v77, v73
	v_fma_f32 v73, v200, s26, -v183
	v_add_f32_e32 v72, v90, v72
	v_exp_f32_e32 v78, v73
	v_fma_f32 v73, v201, s26, -v183
	v_add_f32_e32 v72, v91, v72
	v_exp_f32_e32 v79, v73
	v_fma_f32 v73, v202, s26, -v183
	v_add_f32_e32 v72, v92, v72
	v_exp_f32_e32 v80, v73
	v_fma_f32 v73, v203, s26, -v183
	v_add_f32_e32 v72, v77, v72
	v_exp_f32_e32 v81, v73
	v_fma_f32 v73, v208, s26, -v183
	v_add_f32_e32 v72, v78, v72
	v_exp_f32_e32 v82, v73
	v_fma_f32 v73, v209, s26, -v183
	v_add_f32_e32 v72, v79, v72
	v_exp_f32_e32 v83, v73
	v_fma_f32 v73, v210, s26, -v183
	v_add_f32_e32 v72, v80, v72
	v_exp_f32_e32 v84, v73
	v_add_f32_e32 v72, v81, v72
	v_add_f32_e32 v72, v82, v72
	v_add_f32_e32 v72, v83, v72
	v_fma_f32 v68, v68, s26, -v183
	v_add_f32_e32 v73, v84, v72
	v_exp_f32_e32 v72, v68
	v_fma_f32 v69, v69, s26, -v183
	v_exp_f32_e32 v69, v69
	v_fma_f32 v70, v70, s26, -v183
	v_exp_f32_e32 v70, v70
	v_fma_f32 v71, v71, s26, -v183
	v_add_f32_e32 v68, v72, v73
	v_exp_f32_e32 v71, v71
	v_fma_f32 v73, v211, s26, -v183
	v_exp_f32_e32 v73, v73
	v_fma_f32 v74, v212, s26, -v183
	v_add_f32_e32 v68, v69, v68
	v_exp_f32_e32 v74, v74
	v_sub_f32_e32 v75, v182, v183
	v_add_f32_e32 v68, v70, v68
	v_exp_f32_e32 v75, v75
	v_fma_f32 v76, v213, s26, -v183
	v_add_f32_e32 v68, v71, v68
	v_exp_f32_e32 v76, v76
	v_add_f32_e32 v68, v73, v68
	v_add_f32_e32 v68, v74, v68
	v_add_f32_e32 v68, v75, v68
	v_add_f32_e32 v68, v76, v68
	ds_bpermute_b32 v182, v135, v68
	s_waitcnt lgkmcnt(0)
	v_add_f32_e32 v68, v68, v182
	ds_bpermute_b32 v182, v148, v68
	s_waitcnt lgkmcnt(0)
; #define LAS __attribute__((address_space(3)))
; #define LAS __attribute__((address_space(3)))
; __device__ __forceinline__ unsigned pk2(float lo, float hi) { return pg8::cvt_pk_bf16(lo, hi); }
; #define ATT_LDV(s) do { _Pragma("unroll") for (int dt = 0; dt < 4; ++dt) { vlo[s][dt] = lds_tr_a(vp0 + (s) * 32 * 72 + 16 * dt); vhi[s][dt] = lds_tr_a(vp0 + (s) * 32 * 72 + 16 * 72 + 16 * dt); } } while (0)
; __device__ __forceinline__ void attn_phase(LAS unsigned char* lds, const bf16* PROJ, bf16* CONCAT, const float* sinks) {
;     ...
;                 lsum += __shfl_xor(lsum, 16); lsum += __shfl_xor(lsum, 32); lsum += __builtin_amdgcn_exp2f(sink * LOG2E - mb);
;                 inv[x] = 1.0f / lsum;
;             }
;             f32x4 ot[2][4];
; #pragma unroll
;             for (int x = 0; x < 2; ++x)
; #pragma unroll
;                 for (int dt = 0; dt < 4; ++dt) ot[x][dt] = (f32x4){0.f, 0.f, 0.f, 0.f};
;             const LAS bf16* vp0 = Vs + (16 * kt0 + 4 * fq + (fr >> 2)) * 72 + 4 * (fr & 3);
;             v2u vlo[5][4], vhi[5][4];
;     ...
; #pragma unroll
;             for (int s2 = 0; s2 < 5; ++s2) {
;                 ATT_LDV(s2);
;                 bf16x8 pf[2];
; #pragma unroll
;                 for (int x = 0; x < 2; ++x) { v4u pw; pw.x = pk2(st[x][2 * s2][0], st[x][2 * s2][1]); pw.y = pk2(st[x][2 * s2][2], st[x][2 * s2][3]);
;                     pw.z = pk2(st[x][2 * s2 + 1][0], st[x][2 * s2 + 1][1]); pw.w = pk2(st[x][2 * s2 + 1][2], st[x][2 * s2 + 1][3]); pf[x] = __builtin_bit_cast(bf16x8, pw); }
; #pragma unroll
;                 for (int dt = 0; dt < 4; ++dt) {
;                     const bf16x8 vf = __builtin_bit_cast(bf16x8, (v4u){vlo[s2][dt].x, vlo[s2][dt].y, vhi[s2][dt].x, vhi[s2][dt].y});
; #pragma unroll
;                     for (int x = 0; x < 2; ++x) ot[x][dt] = __builtin_amdgcn_mfma_f32_16x16x32_bf16(vf, pf[x], ot[x][dt], 0, 0, 0);
;                 }
;             }
	v_add_f32_e32 v68, v68, v182
	v_sub_f32_e32 v182, v112, v183
	v_exp_f32_e32 v182, v182
	s_nop 0
	v_add_f32_e32 v68, v182, v68
	v_div_scale_f32 v182, s[70:71], v68, v68, 1.0
	v_rcp_f32_e32 v183, v182
	s_nop 0
	v_fma_f32 v184, -v182, v183, 1.0
	v_fmac_f32_e32 v183, v184, v183
	v_div_scale_f32 v184, vcc, 1.0, v68, 1.0
	v_mul_f32_e32 v185, v184, v183
	v_fma_f32 v186, -v182, v185, v184
	v_fmac_f32_e32 v185, v186, v183
	v_fma_f32 v182, -v182, v185, v184
	v_div_fmas_f32 v182, v182, v183, v185
	v_div_fixup_f32 v68, v182, v68, 1.0
	ds_read_b64_tr_b16 v[182:183], v152 offset:36864
	ds_read_b64_tr_b16 v[186:187], v152 offset:36896
	ds_read_b64_tr_b16 v[184:185], v152 offset:39168
	ds_read_b64_tr_b16 v[188:189], v152 offset:39200
	ds_read_b64_tr_b16 v[200:201], v152 offset:36928
	ds_read_b64_tr_b16 v[202:203], v152 offset:39232
	ds_read_b64_tr_b16 v[208:209], v152 offset:36960
	ds_read_b64_tr_b16 v[210:211], v152 offset:39264
	v_cvt_pk_bf16_f32 v174, v174, v175
	v_cvt_pk_bf16_f32 v175, v176, v177
	v_cvt_pk_bf16_f32 v176, v178, v179
	v_cvt_pk_bf16_f32 v177, v180, v181
	v_cvt_pk_bf16_f32 v178, v1, v1
	v_cvt_pk_bf16_f32 v179, v1, v1
	v_cvt_pk_bf16_f32 v180, v101, v102
	v_cvt_pk_bf16_f32 v181, v103, v113
	s_waitcnt lgkmcnt(5)
	v_mfma_f32_16x16x32_bf16 v[212:215], v[182:185], v[174:177], 0
	v_mfma_f32_16x16x32_bf16 v[182:185], v[182:185], v[178:181], 0
	s_waitcnt lgkmcnt(4)
	v_mfma_f32_16x16x32_bf16 v[216:219], v[186:189], v[174:177], 0
	v_mfma_f32_16x16x32_bf16 v[186:189], v[186:189], v[178:181], 0
	s_waitcnt lgkmcnt(2)
	v_mfma_f32_16x16x32_bf16 v[220:223], v[200:203], v[174:177], 0
	v_mfma_f32_16x16x32_bf16 v[200:203], v[200:203], v[178:181], 0
	s_waitcnt lgkmcnt(0)
	v_mfma_f32_16x16x32_bf16 v[174:177], v[208:211], v[174:177], 0
	v_mfma_f32_16x16x32_bf16 v[178:181], v[208:211], v[178:181], 0
	ds_read_b64_tr_b16 v[208:209], v152 offset:41472
	ds_read_b64_tr_b16 v[224:225], v152 offset:41504
	ds_read_b64_tr_b16 v[210:211], v152 offset:43776
	ds_read_b64_tr_b16 v[226:227], v152 offset:43808
	ds_read_b64_tr_b16 v[228:229], v152 offset:41536
	ds_read_b64_tr_b16 v[230:231], v152 offset:43840
	ds_read_b64_tr_b16 v[232:233], v152 offset:41568
	ds_read_b64_tr_b16 v[234:235], v152 offset:43872
	v_cvt_pk_bf16_f32 v236, v127, v143
	v_cvt_pk_bf16_f32 v237, v145, v157
	v_cvt_pk_bf16_f32 v238, v158, v159
	v_cvt_pk_bf16_f32 v239, v160, v161
	v_cvt_pk_bf16_f32 v94, v93, v94
	v_cvt_pk_bf16_f32 v95, v95, v96
	v_cvt_pk_bf16_f32 v96, v97, v98
	v_cvt_pk_bf16_f32 v97, v99, v100
	v_mov_b32_e32 v143, v1
	s_waitcnt lgkmcnt(5)
	v_mfma_f32_16x16x32_bf16 v[98:101], v[208:211], v[236:239], v[212:215]
	v_mfma_f32_16x16x32_bf16 v[158:161], v[208:211], v[94:97], v[182:185]
	s_waitcnt lgkmcnt(4)
	v_mfma_f32_16x16x32_bf16 v[182:185], v[224:227], v[236:239], v[216:219]
	v_mfma_f32_16x16x32_bf16 v[186:189], v[224:227], v[94:97], v[186:189]
	s_waitcnt lgkmcnt(2)
	v_mfma_f32_16x16x32_bf16 v[208:211], v[228:231], v[236:239], v[220:223]
	v_mfma_f32_16x16x32_bf16 v[200:203], v[228:231], v[94:97], v[200:203]
	s_waitcnt lgkmcnt(0)
	v_mfma_f32_16x16x32_bf16 v[94:97], v[232:235], v[94:97], v[178:181]
	s_nop 2
	ds_read_b64_tr_b16 v[178:179], v152 offset:46080
	ds_read_b64_tr_b16 v[212:213], v152 offset:46112
	ds_read_b64_tr_b16 v[180:181], v152 offset:48384
	ds_read_b64_tr_b16 v[214:215], v152 offset:48416
	ds_read_b64_tr_b16 v[216:217], v152 offset:46144
	ds_read_b64_tr_b16 v[218:219], v152 offset:48448
	ds_read_b64_tr_b16 v[220:221], v152 offset:46176
	ds_read_b64_tr_b16 v[222:223], v152 offset:48480
	v_cvt_pk_bf16_f32 v120, v119, v120
	v_cvt_pk_bf16_f32 v121, v121, v122
	v_mfma_f32_16x16x32_bf16 v[174:177], v[232:235], v[236:239], v[174:177]
	v_cvt_pk_bf16_f32 v122, v123, v124
	v_cvt_pk_bf16_f32 v123, v125, v126
	v_cvt_pk_bf16_f32 v86, v85, v86
	v_cvt_pk_bf16_f32 v87, v87, v88
	v_cvt_pk_bf16_f32 v88, v89, v90
	v_cvt_pk_bf16_f32 v89, v91, v92
	s_waitcnt lgkmcnt(5)
	v_mfma_f32_16x16x32_bf16 v[90:93], v[178:181], v[120:123], v[98:101]
	v_mfma_f32_16x16x32_bf16 v[98:101], v[178:181], v[86:89], v[158:161]
	s_waitcnt lgkmcnt(4)
	v_mfma_f32_16x16x32_bf16 v[124:127], v[212:215], v[120:123], v[182:185]
	v_mfma_f32_16x16x32_bf16 v[158:161], v[212:215], v[86:89], v[186:189]
	s_waitcnt lgkmcnt(2)
	v_mfma_f32_16x16x32_bf16 v[178:181], v[216:219], v[120:123], v[208:211]
	v_mfma_f32_16x16x32_bf16 v[182:185], v[216:219], v[86:89], v[200:203]
	s_waitcnt lgkmcnt(0)
	v_mfma_f32_16x16x32_bf16 v[120:123], v[220:223], v[120:123], v[174:177]
	v_mfma_f32_16x16x32_bf16 v[86:89], v[220:223], v[86:89], v[94:97]
	s_nop 2
	ds_read_b64_tr_b16 v[94:95], v152 offset:50688
	ds_read_b64_tr_b16 v[174:175], v152 offset:50720
	ds_read_b64_tr_b16 v[96:97], v152 offset:52992
	ds_read_b64_tr_b16 v[176:177], v152 offset:53024
	ds_read_b64_tr_b16 v[186:187], v152 offset:50752
	ds_read_b64_tr_b16 v[188:189], v152 offset:53056
	ds_read_b64_tr_b16 v[200:201], v152 offset:50784
	ds_read_b64_tr_b16 v[202:203], v152 offset:53088
	v_cvt_pk_bf16_f32 v208, v109, v110
	v_cvt_pk_bf16_f32 v209, v111, v114
	v_cvt_pk_bf16_f32 v210, v115, v116
	v_cvt_pk_bf16_f32 v211, v117, v118
	v_cvt_pk_bf16_f32 v78, v77, v78
	v_cvt_pk_bf16_f32 v79, v79, v80
	v_cvt_pk_bf16_f32 v80, v81, v82
	v_cvt_pk_bf16_f32 v81, v83, v84
	s_waitcnt lgkmcnt(5)
	v_mfma_f32_16x16x32_bf16 v[82:85], v[94:97], v[208:211], v[90:93]
	v_mfma_f32_16x16x32_bf16 v[90:93], v[94:97], v[78:81], v[98:101]
	s_waitcnt lgkmcnt(4)
	v_mfma_f32_16x16x32_bf16 v[94:97], v[174:177], v[208:211], v[124:127]
	v_mfma_f32_16x16x32_bf16 v[98:101], v[174:177], v[78:81], v[158:161]
	s_waitcnt lgkmcnt(2)
	v_mfma_f32_16x16x32_bf16 v[114:117], v[186:189], v[208:211], v[178:181]
	v_mfma_f32_16x16x32_bf16 v[124:127], v[186:189], v[78:81], v[182:185]
	s_waitcnt lgkmcnt(0)
; __device__ __forceinline__ void attn_phase(LAS unsigned char* lds, const bf16* PROJ, bf16* CONCAT, const float* sinks) {
;     ...
;             const LAS bf16* kp0 = Ks + (16 * kt0 + fr) * 72 + 8 * fq;
;     ...
;             ATT_LDK(0);
; #pragma unroll
;             for (int t = 0; t < 10; ++t) {
;                 if (t + 1 < 10) ATT_LDK(t + 1);
; #pragma unroll
;                 for (int x = 0; x < 2; ++x) {
;                     if (x + 8 - t == 9 || x + 8 - t == -1) { st[x][t] = (f32x4){-1e30f, -1e30f, -1e30f, -1e30f}; continue; }
;                     f32x4 acc = (f32x4){0.f, 0.f, 0.f, 0.f};
;                     acc = __builtin_amdgcn_mfma_f32_16x16x32_bf16(kfr[t][0], qf[2 * p + x][0], acc, 0, 0, 0);
;                     acc = __builtin_amdgcn_mfma_f32_16x16x32_bf16(kfr[t][1], qf[2 * p + x][1], acc, 0, 0, 0);
;     ...
; #pragma unroll
;             for (int s2 = 0; s2 < 5; ++s2) {
;                 ATT_LDV(s2);
;                 bf16x8 pf[2];
; #pragma unroll
;                 for (int x = 0; x < 2; ++x) { v4u pw; pw.x = pk2(st[x][2 * s2][0], st[x][2 * s2][1]); pw.y = pk2(st[x][2 * s2][2], st[x][2 * s2][3]);
;                     pw.z = pk2(st[x][2 * s2 + 1][0], st[x][2 * s2 + 1][1]); pw.w = pk2(st[x][2 * s2 + 1][2], st[x][2 * s2 + 1][3]); pf[x] = __builtin_bit_cast(bf16x8, pw); }
; #pragma unroll
;                 for (int dt = 0; dt < 4; ++dt) {
;                     const bf16x8 vf = __builtin_bit_cast(bf16x8, (v4u){vlo[s2][dt].x, vlo[s2][dt].y, vhi[s2][dt].x, vhi[s2][dt].y});
; #pragma unroll
;                     for (int x = 0; x < 2; ++x) ot[x][dt] = __builtin_amdgcn_mfma_f32_16x16x32_bf16(vf, pf[x], ot[x][dt], 0, 0, 0);
;                 }
;             }
;     ...
; #pragma unroll
;             for (int x = 0; x < 2; ++x) {
;                 LAS bf16* stg = (LAS bf16*)(lds + 73728) + (wave * 2 + x) * (16 * 72);
; #pragma unroll
;                 for (int dt = 0; dt < 4; ++dt) *(LAS v2u*)(stg + fr * 72 + 16 * dt + 4 * fq) = (v2u){pk2(ot[x][dt][0] * inv[x], ot[x][dt][1] * inv[x]), pk2(ot[x][dt][2] * inv[x], ot[x][dt][3] * inv[x])};
;                 bf16* op = CONCAT + (qrow0 - fr + 16 * (2 * p + x)) * DM + h * 64;
; #pragma unroll
;                 for (int i = 0; i < 2; ++i) { const int row = 8 * i + (lane >> 3), chn = lane & 7;
;                     *(v4u*)(op + (size_t)row * DM + chn * 8) = *(const LAS v4u*)(stg + row * 72 + chn * 8); }
;             }
	v_mfma_f32_16x16x32_bf16 v[78:81], v[200:203], v[78:81], v[86:89]
	s_nop 2
	ds_read_b64_tr_b16 v[86:87], v152 offset:55296
	ds_read_b64_tr_b16 v[158:159], v152 offset:55328
	ds_read_b64_tr_b16 v[88:89], v152 offset:57600
	ds_read_b64_tr_b16 v[160:161], v152 offset:57632
	ds_read_b64_tr_b16 v[174:175], v152 offset:55360
	ds_read_b64_tr_b16 v[176:177], v152 offset:57664
	ds_read_b64_tr_b16 v[178:179], v152 offset:55392
	ds_read_b64_tr_b16 v[180:181], v152 offset:57696
	v_cvt_pk_bf16_f32 v106, v105, v106
	v_cvt_pk_bf16_f32 v107, v107, v108
	v_cvt_pk_bf16_f32 v108, v1, v1
	v_cvt_pk_bf16_f32 v109, v1, v1
	v_cvt_pk_bf16_f32 v182, v72, v69
	v_cvt_pk_bf16_f32 v183, v70, v71
	v_cvt_pk_bf16_f32 v184, v73, v74
	v_mfma_f32_16x16x32_bf16 v[118:121], v[200:203], v[208:211], v[120:123]
	v_cvt_pk_bf16_f32 v185, v75, v76
	s_waitcnt lgkmcnt(5)
	v_mfma_f32_16x16x32_bf16 v[70:73], v[86:89], v[106:109], v[82:85]
	s_waitcnt lgkmcnt(4)
	v_mfma_f32_16x16x32_bf16 v[82:85], v[158:161], v[106:109], v[94:97]
	v_mfma_f32_16x16x32_bf16 v[74:77], v[86:89], v[182:185], v[90:93]
	s_nop 4
	v_mul_f32_e32 v69, v104, v70
	v_mul_f32_e32 v70, v104, v71
	v_mul_f32_e32 v71, v104, v73
	s_waitcnt lgkmcnt(2)
	v_mfma_f32_16x16x32_bf16 v[90:93], v[174:177], v[106:109], v[114:117]
	v_cvt_pk_bf16_f32 v70, v69, v70
	v_mul_f32_e32 v69, v104, v72
	v_cvt_pk_bf16_f32 v71, v69, v71
	v_mfma_f32_16x16x32_bf16 v[86:89], v[158:161], v[182:185], v[98:101]
	ds_write_b64 v150, v[70:71]
	v_mul_f32_e32 v69, v104, v82
	v_mul_f32_e32 v70, v104, v83
	s_waitcnt lgkmcnt(1)
	v_mfma_f32_16x16x32_bf16 v[98:101], v[178:181], v[106:109], v[118:121]
	v_mul_f32_e32 v71, v104, v85
	v_cvt_pk_bf16_f32 v70, v69, v70
	v_mul_f32_e32 v69, v104, v84
	v_cvt_pk_bf16_f32 v71, v69, v71
	ds_write_b64 v150, v[70:71] offset:32
	v_mul_f32_e32 v69, v104, v90
	v_mul_f32_e32 v70, v104, v91
	v_mul_f32_e32 v71, v104, v93
	v_cvt_pk_bf16_f32 v70, v69, v70
	v_mul_f32_e32 v69, v104, v92
	v_cvt_pk_bf16_f32 v71, v69, v71
	ds_write_b64 v150, v[70:71] offset:64
	v_mul_f32_e32 v69, v104, v98
	v_mul_f32_e32 v70, v104, v99
	v_mul_f32_e32 v71, v104, v101
	v_cvt_pk_bf16_f32 v70, v69, v70
	v_mul_f32_e32 v69, v104, v100
	v_cvt_pk_bf16_f32 v71, v69, v71
	ds_write_b64 v150, v[70:71] offset:96
	v_mov_b32_e32 v71, s37
	v_or_b32_e32 v70, s36, v134
	v_lshlrev_b64 v[70:71], 11, v[70:71]
	v_lshl_add_u64 v[114:115], v[146:147], 0, v[70:71]
	ds_read_b128 v[70:73], v153
	v_lshl_add_u64 v[82:83], v[114:115], 0, v[0:1]
	v_mfma_f32_16x16x32_bf16 v[94:97], v[174:177], v[182:185], v[124:127]
	v_mul_f32_e32 v69, v68, v74
	s_mov_b64 s[36:37], 0x8000
	s_waitcnt lgkmcnt(0)
	global_store_dwordx4 v[82:83], v[70:73], off
	ds_read_b128 v[70:73], v154
	v_lshl_add_u64 v[82:83], v[114:115], 0, v[142:143]
	v_mfma_f32_16x16x32_bf16 v[78:81], v[178:181], v[182:185], v[78:81]
	s_waitcnt lgkmcnt(0)
	global_store_dwordx4 v[82:83], v[70:73], off
	s_nop 1
	v_mul_f32_e32 v70, v68, v75
	v_cvt_pk_bf16_f32 v70, v69, v70
	v_mul_f32_e32 v69, v68, v76
	v_mul_f32_e32 v71, v68, v77
	v_cvt_pk_bf16_f32 v71, v69, v71
	ds_write_b64 v150, v[70:71] offset:2304
	v_mul_f32_e32 v69, v68, v86
	v_mul_f32_e32 v70, v68, v87
	v_cvt_pk_bf16_f32 v70, v69, v70
	v_mul_f32_e32 v69, v68, v88
	v_mul_f32_e32 v71, v68, v89
	v_cvt_pk_bf16_f32 v71, v69, v71
	ds_write_b64 v150, v[70:71] offset:2336
	v_mul_f32_e32 v69, v68, v94
	v_mul_f32_e32 v70, v68, v95
	v_cvt_pk_bf16_f32 v70, v69, v70
	v_mul_f32_e32 v69, v68, v96
	v_mul_f32_e32 v71, v68, v97
	v_cvt_pk_bf16_f32 v71, v69, v71
	ds_write_b64 v150, v[70:71] offset:2368
	v_mul_f32_e32 v69, v68, v78
	v_mul_f32_e32 v70, v68, v79
	v_cvt_pk_bf16_f32 v70, v69, v70
	v_mul_f32_e32 v69, v68, v80
	v_mul_f32_e32 v68, v68, v81
	v_cvt_pk_bf16_f32 v71, v69, v68
	ds_write_b64 v150, v[70:71] offset:2400
	ds_read_b128 v[68:71], v153 offset:2304
	v_lshl_add_u64 v[72:73], v[114:115], 0, s[36:37]
	v_lshl_add_u64 v[74:75], v[72:73], 0, v[0:1]
	v_lshl_add_u64 v[72:73], v[72:73], 0, v[142:143]
	s_waitcnt lgkmcnt(0)
	global_store_dwordx4 v[74:75], v[68:71], off
	ds_read_b128 v[68:71], v154 offset:2304
	s_waitcnt lgkmcnt(0)
	global_store_dwordx4 v[72:73], v[68:71], off
	ds_read_b128 v[68:71], v155
	ds_read_b128 v[72:75], v155 offset:64
	ds_read_b128 v[76:79], v155 offset:2304
	ds_read_b128 v[80:83], v155 offset:2368
	s_waitcnt lgkmcnt(3)
	v_mfma_f32_16x16x32_bf16 v[68:71], v[68:71], v[48:51], 0
	s_waitcnt lgkmcnt(2)
	v_mfma_f32_16x16x32_bf16 v[116:119], v[72:75], v[44:47], v[68:71]
	s_nop 5
	ds_read_b128 v[68:71], v155 offset:4608
	ds_read_b128 v[72:75], v155 offset:4672
	v_cndmask_b32_e64 v113, v197, v116, s[50:51]
	s_waitcnt lgkmcnt(3)
	v_mfma_f32_16x16x32_bf16 v[84:87], v[76:79], v[48:51], 0
	v_cndmask_b32_e64 v145, v197, v117, s[52:53]
	v_max3_f32 v116, v113, s78, v145
	v_cndmask_b32_e64 v118, v197, v118, s[54:55]
	v_mfma_f32_16x16x32_bf16 v[76:79], v[76:79], v[56:59], 0
	v_cndmask_b32_e64 v119, v197, v119, s[56:57]
	v_max3_f32 v116, v116, v118, v119
	s_waitcnt lgkmcnt(2)
	v_mfma_f32_16x16x32_bf16 v[120:123], v[80:83], v[44:47], v[84:87]
	v_mfma_f32_16x16x32_bf16 v[80:83], v[80:83], v[52:55], v[76:79]
	s_nop 2
	ds_read_b128 v[76:79], v155 offset:6912
	ds_read_b128 v[88:91], v155 offset:6976
	s_nop 1
	v_cndmask_b32_e64 v120, v197, v120, s[60:61]
	v_cndmask_b32_e64 v121, v197, v121, s[60:61]
	s_waitcnt lgkmcnt(3)
	v_mfma_f32_16x16x32_bf16 v[84:87], v[68:71], v[48:51], 0
	v_max3_f32 v116, v116, v120, v121
	v_cndmask_b32_e64 v122, v197, v122, s[60:61]
	v_cndmask_b32_e64 v123, v197, v123, s[60:61]
	v_mfma_f32_16x16x32_bf16 v[68:71], v[68:71], v[56:59], 0
	v_max3_f32 v116, v116, v122, v123
	v_cndmask_b32_e64 v82, v197, v82, s[54:55]
	v_cndmask_b32_e64 v83, v197, v83, s[56:57]
	s_waitcnt lgkmcnt(2)
; #define LAS __attribute__((address_space(3)))
; #define LAS __attribute__((address_space(3)))
; #define ATT_LDK(t) do { kfr[t][0] = *(const LAS bf16x8*)(kp0 + (t) * 16 * 72); kfr[t][1] = *(const LAS bf16x8*)(kp0 + (t) * 16 * 72 + 32); } while (0)
; __device__ __forceinline__ void attn_phase(LAS unsigned char* lds, const bf16* PROJ, bf16* CONCAT, const float* sinks) {
;     ...
;     const bool xmap = (gridDim.x == 256);
;     ...
;             const LAS bf16* kp0 = Ks + (16 * kt0 + fr) * 72 + 8 * fq;
;     ...
;             ATT_LDK(0);
; #pragma unroll
;             for (int t = 0; t < 10; ++t) {
;                 if (t + 1 < 10) ATT_LDK(t + 1);
; #pragma unroll
;                 for (int x = 0; x < 2; ++x) {
;                     if (x + 8 - t == 9 || x + 8 - t == -1) { st[x][t] = (f32x4){-1e30f, -1e30f, -1e30f, -1e30f}; continue; }
;                     f32x4 acc = (f32x4){0.f, 0.f, 0.f, 0.f};
;                     acc = __builtin_amdgcn_mfma_f32_16x16x32_bf16(kfr[t][0], qf[2 * p + x][0], acc, 0, 0, 0);
;                     acc = __builtin_amdgcn_mfma_f32_16x16x32_bf16(kfr[t][1], qf[2 * p + x][1], acc, 0, 0, 0);
;                     st[x][t] = acc;
;                 }
;             }
	v_mfma_f32_16x16x32_bf16 v[124:127], v[72:75], v[44:47], v[84:87]
	v_mfma_f32_16x16x32_bf16 v[84:87], v[72:75], v[52:55], v[68:71]
	s_nop 2
	ds_read_b128 v[68:71], v155 offset:9216
	ds_read_b128 v[72:75], v155 offset:9280
	s_nop 1
	v_cndmask_b32_e64 v124, v197, v124, s[58:59]
	v_cndmask_b32_e64 v125, v197, v125, s[58:59]
	s_waitcnt lgkmcnt(3)
	v_mfma_f32_16x16x32_bf16 v[92:95], v[76:79], v[48:51], 0
	v_max3_f32 v116, v116, v124, v125
	v_cndmask_b32_e64 v126, v197, v126, s[58:59]
	v_cndmask_b32_e64 v127, v197, v127, s[58:59]
	v_mfma_f32_16x16x32_bf16 v[76:79], v[76:79], v[56:59], 0
	v_max3_f32 v116, v116, v126, v127
	v_cndmask_b32_e64 v84, v197, v84, s[58:59]
	v_cndmask_b32_e64 v85, v197, v85, s[58:59]
	s_waitcnt lgkmcnt(2)
	v_mfma_f32_16x16x32_bf16 v[158:161], v[88:91], v[44:47], v[92:95]
	v_cndmask_b32_e64 v86, v197, v86, s[58:59]
	v_cndmask_b32_e64 v87, v197, v87, s[58:59]
	v_mfma_f32_16x16x32_bf16 v[88:91], v[88:91], v[52:55], v[76:79]
	s_nop 2
	ds_read_b128 v[76:79], v155 offset:11520
	ds_read_b128 v[96:99], v155 offset:11584
	v_cndmask_b32_e64 v146, v197, v158, s[58:59]
	s_nop 1
	v_cndmask_b32_e64 v88, v197, v88, s[58:59]
	s_waitcnt lgkmcnt(3)
	v_mfma_f32_16x16x32_bf16 v[92:95], v[68:71], v[48:51], 0
	v_cndmask_b32_e64 v89, v197, v89, s[58:59]
	v_cndmask_b32_e64 v90, v197, v90, s[58:59]
	v_cndmask_b32_e64 v91, v197, v91, s[58:59]
	v_mfma_f32_16x16x32_bf16 v[68:71], v[68:71], v[56:59], 0
	s_waitcnt lgkmcnt(2)
	v_mfma_f32_16x16x32_bf16 v[174:177], v[72:75], v[44:47], v[92:95]
	v_mfma_f32_16x16x32_bf16 v[92:95], v[72:75], v[52:55], v[68:71]
	s_nop 4
	ds_read_b128 v[68:71], v155 offset:13824
	ds_read_b128 v[72:75], v155 offset:13888
	v_cndmask_b32_e64 v190, v197, v177, s[58:59]
	v_cndmask_b32_e64 v92, v197, v92, s[58:59]
	s_waitcnt lgkmcnt(3)
	v_mfma_f32_16x16x32_bf16 v[100:103], v[76:79], v[48:51], 0
	v_cndmask_b32_e64 v93, v197, v93, s[58:59]
	v_cndmask_b32_e64 v94, v197, v94, s[58:59]
	v_cndmask_b32_e64 v95, v197, v95, s[58:59]
	v_mfma_f32_16x16x32_bf16 v[76:79], v[76:79], v[56:59], 0
	s_waitcnt lgkmcnt(2)
	v_mfma_f32_16x16x32_bf16 v[178:181], v[96:99], v[44:47], v[100:103]
	v_mfma_f32_16x16x32_bf16 v[96:99], v[96:99], v[52:55], v[76:79]
	s_nop 4
	ds_read_b128 v[76:79], v155 offset:16128
	ds_read_b128 v[100:103], v155 offset:16192
	ds_read_b128 v[182:185], v155 offset:18432
	ds_read_b128 v[186:189], v155 offset:18496
	v_cndmask_b32_e64 v191, v197, v178, s[58:59]
	s_waitcnt lgkmcnt(5)
	v_mfma_f32_16x16x32_bf16 v[104:107], v[68:71], v[48:51], 0
	v_cndmask_b32_e64 v199, v197, v179, s[58:59]
	v_mfma_f32_16x16x32_bf16 v[68:71], v[68:71], v[56:59], 0
	s_waitcnt lgkmcnt(4)
	v_mfma_f32_16x16x32_bf16 v[108:111], v[72:75], v[44:47], v[104:107]
	v_mfma_f32_16x16x32_bf16 v[68:71], v[72:75], v[52:55], v[68:71]
	s_waitcnt lgkmcnt(3)
	v_mfma_f32_16x16x32_bf16 v[72:75], v[76:79], v[48:51], 0
	s_waitcnt lgkmcnt(2)
	v_mfma_f32_16x16x32_bf16 v[104:107], v[100:103], v[44:47], v[72:75]
	v_mfma_f32_16x16x32_bf16 v[72:75], v[76:79], v[56:59], 0
	s_waitcnt lgkmcnt(1)
	v_mfma_f32_16x16x32_bf16 v[76:79], v[182:185], v[48:51], 0
	v_mfma_f32_16x16x32_bf16 v[72:75], v[100:103], v[52:55], v[72:75]
	ds_read_b128 v[100:103], v155 offset:20736
	ds_read_b128 v[200:203], v155 offset:20800
	s_waitcnt lgkmcnt(2)
	v_mfma_f32_16x16x32_bf16 v[208:211], v[186:189], v[44:47], v[76:79]
	v_mfma_f32_16x16x32_bf16 v[76:79], v[182:185], v[56:59], 0
	v_cndmask_b32_e64 v184, v197, v159, s[58:59]
	v_max3_f32 v116, v116, v146, v184
	v_cndmask_b32_e64 v185, v197, v160, s[58:59]
	v_mfma_f32_16x16x32_bf16 v[76:79], v[186:189], v[52:55], v[76:79]
	v_cndmask_b32_e64 v186, v197, v161, s[58:59]
	v_max3_f32 v116, v116, v185, v186
	v_cndmask_b32_e64 v187, v197, v174, s[58:59]
	s_waitcnt lgkmcnt(1)
	v_mfma_f32_16x16x32_bf16 v[100:103], v[100:103], v[56:59], 0
	v_cndmask_b32_e64 v188, v197, v175, s[58:59]
	v_max3_f32 v116, v116, v187, v188
	v_cndmask_b32_e64 v189, v197, v176, s[58:59]
	v_max3_f32 v116, v116, v189, v190
	s_waitcnt lgkmcnt(0)
	v_mfma_f32_16x16x32_bf16 v[100:103], v[200:203], v[52:55], v[100:103]
	s_andn2_b64 vcc, exec, s[64:65]
	s_cbranch_vccnz .Lattn_q_skip
	s_lshr_b32 s98, s23, 1
	s_and_b64 vcc, s[80:81], exec
	s_cselect_b32 s98, s98, s17
	s_and_b32 s99, s16, 32
	s_bfe_u32 s100, s23, 0x50003
	s_or_b32 s99, s99, s100
	s_lshl_b32 s99, s99, 1
	s_and_b64 vcc, s[80:81], exec
	s_cselect_b32 s99, s99, s17
	s_and_b32 s100, s16, 0x80
	s_and_b32 s101, s17, 0xffffff00
	s_or_b32 s100, s101, s100
	s_and_b64 vcc, s[80:81], exec
	s_cselect_b32 s100, s100, s17
	s_ashr_i32 s100, s100, 7
	s_ashr_i32 s101, s100, 31
	s_lshl_b32 s99, s99, 6
	s_lshl_b64 s[100:101], s[100:101], 13
	s_and_b32 s99, s99, 0x1f80
	s_or_b32 s99, s100, s99
	v_or_b32_e32 v30, s99, v132
	s_lshl_b32 s99, s98, 2
	s_and_b32 s99, s99, 4
	v_add_lshl_u32 v28, s99, v133, 6
	v_ashrrev_i32_e32 v29, 31, v28
	v_lshl_add_u64 v[28:29], v[28:29], 1, v[140:141]
	v_mad_u64_u32 v[52:53], vcc, v30, s85, v[28:29]
	v_mad_i32_i24 v53, s101, v195, v53
	v_add_co_u32_e32 v36, vcc, 0xa000, v52
	global_load_dwordx4 v[32:35], v[52:53], off nt
	global_load_dwordx4 v[28:31], v[52:53], off offset:64 nt
	v_addc_co_u32_e32 v37, vcc, 0, v53, vcc
	v_add_co_u32_e32 v44, vcc, 0x14000, v52
	global_load_dwordx4 v[40:43], v[36:37], off nt
	s_nop 0
	global_load_dwordx4 v[36:39], v[36:37], off offset:64 nt
	v_addc_co_u32_e32 v45, vcc, 0, v53, vcc
	v_add_co_u32_e32 v52, vcc, 0x1e000, v52
	global_load_dwordx4 v[48:51], v[44:45], off nt
	s_nop 0
	global_load_dwordx4 v[44:47], v[44:45], off offset:64 nt
	v_addc_co_u32_e32 v53, vcc, 0, v53, vcc
	global_load_dwordx4 v[56:59], v[52:53], off nt
	s_nop 0
	global_load_dwordx4 v[52:55], v[52:53], off offset:64 nt
; __device__ __forceinline__ void attn_phase(LAS unsigned char* lds, const bf16* PROJ, bf16* CONCAT, const float* sinks) {
;     ...
;             float inv[2];
; #pragma unroll
;             for (int x = 0; x < 2; ++x) {
;                 float mx = -1e30f;
; #pragma unroll
;                 for (int t = 0; t < 10; ++t) {
;                     const int D = x + 8 - t;
;                     if (D == 9 || D == -1) continue;
;                     const bool tile_off = firstblk && (kt0 + t < 8);
; #pragma unroll
;                     for (int r = 0; r < 4; ++r) { const int dl = fr - 4 * fq - r;
;                         bool valid = !tile_off;
;                         if (D == 8) valid = valid && (dl < 0);
;                         if (D == 0) valid = valid && (dl >= 0);
;                         const float sv = valid ? st[x][t][r] : -1e30f; st[x][t][r] = sv; mx = fmaxf(mx, sv); }
;                 }
;                 mx = fmaxf(mx, __shfl_xor(mx, 16)); mx = fmaxf(mx, __shfl_xor(mx, 32)); mx = fmaxf(mx, sink);
;                 const float mb = mx * LOG2E;
;                 float lsum = 0.f;
; #pragma unroll
;                 for (int t = 0; t < 10; ++t) {
;                     const int D = x + 8 - t;
;                     if (D == 9 || D == -1) { st[x][t] = (f32x4){0.f, 0.f, 0.f, 0.f}; continue; }
; #pragma unroll
;                     for (int r = 0; r < 4; ++r) { const float pe = __builtin_amdgcn_exp2f(st[x][t][r] * LOG2E - mb); st[x][t][r] = pe; lsum += pe; }
;                 }
;                 lsum += __shfl_xor(lsum, 16); lsum += __shfl_xor(lsum, 32); lsum += __builtin_amdgcn_exp2f(sink * LOG2E - mb);
;                 inv[x] = 1.0f / lsum;
.Lattn_q_skip:
	v_max3_f32 v116, v116, v191, v199
	v_cndmask_b32_e64 v200, v197, v180, s[58:59]
	v_cndmask_b32_e64 v201, v197, v181, s[58:59]
	v_max3_f32 v116, v116, v200, v201
	v_max3_f32 v116, v116, v108, v109
	v_max3_f32 v116, v116, v110, v111
	v_max3_f32 v116, v116, v104, v105
	v_max3_f32 v116, v116, v106, v107
	v_cndmask_b32_e64 v202, v208, v197, s[38:39]
	v_cndmask_b32_e64 v203, v197, v209, s[48:49]
	v_max3_f32 v117, v116, v202, v203
	v_cndmask_b32_e64 v208, v210, v197, s[42:43]
	v_cndmask_b32_e64 v116, v211, v197, s[44:45]
	v_max3_f32 v117, v117, v208, v116
	ds_bpermute_b32 v147, v135, v117
	s_waitcnt lgkmcnt(0)
	v_max_f32_e32 v147, v147, v147
	v_max_f32_e32 v117, v117, v147
	ds_bpermute_b32 v147, v148, v117
	s_waitcnt lgkmcnt(0)
	v_max3_f32 v117, v117, v147, v144
	v_pk_mul_f32 v[116:117], v[116:117], s[26:27] op_sel_hi:[1,0]
	s_nop 0
	v_fma_f32 v113, v113, s26, -v117
	v_exp_f32_e32 v176, v113
	v_fma_f32 v145, v145, s26, -v117
	v_exp_f32_e32 v177, v145
	v_fma_f32 v118, v118, s26, -v117
	v_exp_f32_e32 v178, v118
	v_fma_f32 v118, v119, s26, -v117
	v_exp_f32_e32 v179, v118
	v_fma_f32 v118, v120, s26, -v117
	v_add_f32_e32 v113, 0, v176
	v_exp_f32_e32 v180, v118
	v_fma_f32 v118, v121, s26, -v117
	v_add_f32_e32 v113, v177, v113
	v_exp_f32_e32 v181, v118
	v_fma_f32 v118, v122, s26, -v117
	v_add_f32_e32 v113, v178, v113
	v_exp_f32_e32 v182, v118
	v_fma_f32 v118, v123, s26, -v117
	v_add_f32_e32 v113, v179, v113
	v_exp_f32_e32 v183, v118
	v_fma_f32 v118, v124, s26, -v117
	v_add_f32_e32 v113, v180, v113
	v_exp_f32_e32 v147, v118
	v_fma_f32 v118, v125, s26, -v117
	v_add_f32_e32 v113, v181, v113
	v_exp_f32_e32 v157, v118
	v_fma_f32 v118, v126, s26, -v117
	v_add_f32_e32 v113, v182, v113
	v_exp_f32_e32 v158, v118
	v_fma_f32 v118, v127, s26, -v117
	v_add_f32_e32 v113, v183, v113
	v_exp_f32_e32 v159, v118
	v_fma_f32 v118, v146, s26, -v117
	v_add_f32_e32 v113, v147, v113
	v_exp_f32_e32 v160, v118
	v_fma_f32 v118, v184, s26, -v117
	v_add_f32_e32 v113, v157, v113
	v_exp_f32_e32 v161, v118
	v_fma_f32 v118, v185, s26, -v117
	v_add_f32_e32 v113, v158, v113
	v_exp_f32_e32 v174, v118
	v_fma_f32 v118, v186, s26, -v117
	v_add_f32_e32 v113, v159, v113
	v_exp_f32_e32 v175, v118
	v_fma_f32 v118, v187, s26, -v117
	v_add_f32_e32 v113, v160, v113
	v_exp_f32_e32 v122, v118
	v_fma_f32 v118, v188, s26, -v117
	v_add_f32_e32 v113, v161, v113
	v_exp_f32_e32 v123, v118
	v_fma_f32 v118, v189, s26, -v117
	v_add_f32_e32 v113, v174, v113
	v_exp_f32_e32 v124, v118
	v_fma_f32 v118, v190, s26, -v117
	v_add_f32_e32 v113, v175, v113
	v_exp_f32_e32 v125, v118
	v_fma_f32 v118, v191, s26, -v117
	v_add_f32_e32 v113, v122, v113
	v_exp_f32_e32 v126, v118
	v_fma_f32 v118, v199, s26, -v117
	v_add_f32_e32 v113, v123, v113
	v_exp_f32_e32 v127, v118
	v_fma_f32 v118, v200, s26, -v117
	v_add_f32_e32 v113, v124, v113
	v_exp_f32_e32 v145, v118
	v_fma_f32 v118, v201, s26, -v117
	v_add_f32_e32 v113, v125, v113
	v_exp_f32_e32 v146, v118
	v_add_f32_e32 v113, v126, v113
	v_add_f32_e32 v113, v127, v113
	v_add_f32_e32 v113, v145, v113
	v_fma_f32 v108, v108, s26, -v117
	v_add_f32_e32 v118, v146, v113
	v_exp_f32_e32 v113, v108
	v_fma_f32 v109, v109, s26, -v117
	v_exp_f32_e32 v109, v109
	v_fma_f32 v110, v110, s26, -v117
	v_exp_f32_e32 v110, v110
	v_fma_f32 v111, v111, s26, -v117
	v_exp_f32_e32 v111, v111
	v_fma_f32 v104, v104, s26, -v117
	v_add_f32_e32 v108, v113, v118
	v_exp_f32_e32 v118, v104
	v_fma_f32 v105, v105, s26, -v117
	v_add_f32_e32 v108, v109, v108
	v_exp_f32_e32 v119, v105
	v_fma_f32 v105, v106, s26, -v117
	v_add_f32_e32 v108, v110, v108
	v_exp_f32_e32 v120, v105
	v_fma_f32 v105, v107, s26, -v117
	v_add_f32_e32 v108, v111, v108
	v_exp_f32_e32 v121, v105
	v_fma_f32 v105, v202, s26, -v117
	v_add_f32_e32 v104, v118, v108
	v_exp_f32_e32 v105, v105
	v_fma_f32 v106, v203, s26, -v117
	v_add_f32_e32 v104, v119, v104
	v_exp_f32_e32 v106, v106
	v_fma_f32 v107, v208, s26, -v117
	v_add_f32_e32 v104, v120, v104
	v_exp_f32_e32 v107, v107
	v_sub_f32_e32 v108, v116, v117
	v_add_f32_e32 v104, v121, v104
	v_exp_f32_e32 v108, v108
	v_add_f32_e32 v104, v105, v104
	v_add_f32_e32 v104, v106, v104
	v_add_f32_e32 v104, v107, v104
	v_add_f32_e32 v104, v108, v104
	ds_bpermute_b32 v116, v135, v104
	v_cndmask_b32_e64 v188, v197, v97, s[58:59]
	v_cndmask_b32_e64 v189, v197, v98, s[58:59]
	v_cndmask_b32_e64 v190, v197, v99, s[58:59]
	v_cndmask_b32_e64 v191, v100, v197, s[38:39]
	s_waitcnt lgkmcnt(0)
	v_add_f32_e32 v104, v104, v116
	ds_bpermute_b32 v116, v148, v104
	v_cndmask_b32_e64 v199, v197, v101, s[48:49]
	v_cndmask_b32_e64 v200, v103, v197, s[44:45]
	s_waitcnt lgkmcnt(0)
	v_add_f32_e32 v104, v104, v116
	v_sub_f32_e32 v116, v112, v117
	v_exp_f32_e32 v116, v116
	s_nop 0
	v_add_f32_e32 v104, v116, v104
	v_div_scale_f32 v116, s[36:37], v104, v104, 1.0
	v_rcp_f32_e32 v117, v116
	s_nop 0
	v_fma_f32 v184, -v116, v117, 1.0
	v_fmac_f32_e32 v117, v184, v117
	v_div_scale_f32 v184, vcc, 1.0, v104, 1.0
	v_mul_f32_e32 v185, v184, v117
	v_fma_f32 v186, -v116, v185, v184
	v_fmac_f32_e32 v185, v186, v117
	v_fma_f32 v116, -v116, v185, v184
	v_div_fmas_f32 v116, v116, v117, v185
	v_div_fixup_f32 v104, v116, v104, 1.0
	v_cndmask_b32_e64 v116, v197, v80, s[50:51]
	v_cndmask_b32_e64 v117, v197, v81, s[52:53]
	v_max3_f32 v80, v116, s78, v117
	v_max3_f32 v80, v80, v82, v83
	v_max3_f32 v80, v80, v84, v85
	v_max3_f32 v80, v80, v86, v87
	v_max3_f32 v80, v80, v88, v89
	v_max3_f32 v80, v80, v90, v91
	v_max3_f32 v80, v80, v92, v93
	v_max3_f32 v80, v80, v94, v95
	v_cndmask_b32_e64 v185, v197, v96, s[58:59]
	v_max3_f32 v80, v80, v185, v188
	v_max3_f32 v80, v80, v189, v190
	v_max3_f32 v80, v80, v68, v69
	v_max3_f32 v80, v80, v70, v71
	v_max3_f32 v80, v80, v72, v73
	v_max3_f32 v80, v80, v74, v75
	v_max3_f32 v80, v80, v76, v77
	v_max3_f32 v81, v80, v78, v79
	v_cndmask_b32_e64 v80, v102, v197, s[42:43]
	v_max3_f32 v81, v81, v191, v199
	v_max3_f32 v81, v81, v80, v200
	ds_bpermute_b32 v96, v135, v81
	s_waitcnt lgkmcnt(0)
; #define LAS __attribute__((address_space(3)))
; __device__ __forceinline__ void attn_phase(LAS unsigned char* lds, const bf16* PROJ, bf16* CONCAT, const float* sinks) {
;     ...
;             float inv[2];
; #pragma unroll
;             for (int x = 0; x < 2; ++x) {
;                 float mx = -1e30f;
; #pragma unroll
;                 for (int t = 0; t < 10; ++t) {
;                     const int D = x + 8 - t;
;                     if (D == 9 || D == -1) continue;
;                     const bool tile_off = firstblk && (kt0 + t < 8);
; #pragma unroll
;                     for (int r = 0; r < 4; ++r) { const int dl = fr - 4 * fq - r;
;                         bool valid = !tile_off;
;                         if (D == 8) valid = valid && (dl < 0);
;                         if (D == 0) valid = valid && (dl >= 0);
;                         const float sv = valid ? st[x][t][r] : -1e30f; st[x][t][r] = sv; mx = fmaxf(mx, sv); }
;                 }
;                 mx = fmaxf(mx, __shfl_xor(mx, 16)); mx = fmaxf(mx, __shfl_xor(mx, 32)); mx = fmaxf(mx, sink);
;                 const float mb = mx * LOG2E;
;                 float lsum = 0.f;
; #pragma unroll
;                 for (int t = 0; t < 10; ++t) {
;                     const int D = x + 8 - t;
;                     if (D == 9 || D == -1) { st[x][t] = (f32x4){0.f, 0.f, 0.f, 0.f}; continue; }
; #pragma unroll
;                     for (int r = 0; r < 4; ++r) { const float pe = __builtin_amdgcn_exp2f(st[x][t][r] * LOG2E - mb); st[x][t][r] = pe; lsum += pe; }
;                 }
;                 lsum += __shfl_xor(lsum, 16); lsum += __shfl_xor(lsum, 32); lsum += __builtin_amdgcn_exp2f(sink * LOG2E - mb);
;                 inv[x] = 1.0f / lsum;
;             }
;             f32x4 ot[2][4];
; #pragma unroll
;             for (int x = 0; x < 2; ++x)
; #pragma unroll
;                 for (int dt = 0; dt < 4; ++dt) ot[x][dt] = (f32x4){0.f, 0.f, 0.f, 0.f};
;             const LAS bf16* vp0 = Vs + (16 * kt0 + 4 * fq + (fr >> 2)) * 72 + 4 * (fr & 3);
;             v2u vlo[5][4], vhi[5][4];
;     ...
; #pragma unroll
;             for (int s2 = 0; s2 < 5; ++s2) {
;                 ATT_LDV(s2);
;                 bf16x8 pf[2];
; #pragma unroll
;                 for (int x = 0; x < 2; ++x) { v4u pw; pw.x = pk2(st[x][2 * s2][0], st[x][2 * s2][1]); pw.y = pk2(st[x][2 * s2][2], st[x][2 * s2][3]);
	v_max_f32_e32 v96, v96, v96
	v_max_f32_e32 v81, v81, v96
	ds_bpermute_b32 v96, v148, v81
	s_waitcnt lgkmcnt(0)
	v_max3_f32 v81, v81, v96, v144
	v_pk_mul_f32 v[186:187], v[80:81], s[26:27] op_sel_hi:[1,0]
	s_nop 0
	v_fma_f32 v80, v116, s26, -v187
	v_exp_f32_e32 v116, v80
	v_fma_f32 v81, v117, s26, -v187
	v_exp_f32_e32 v117, v81
	v_fma_f32 v81, v82, s26, -v187
	v_exp_f32_e32 v144, v81
	v_fma_f32 v81, v83, s26, -v187
	v_exp_f32_e32 v184, v81
	v_fma_f32 v81, v84, s26, -v187
	v_add_f32_e32 v80, 0, v116
	v_exp_f32_e32 v96, v81
	v_fma_f32 v81, v85, s26, -v187
	v_add_f32_e32 v80, v117, v80
	v_exp_f32_e32 v97, v81
	v_fma_f32 v81, v86, s26, -v187
	v_add_f32_e32 v80, v144, v80
	v_exp_f32_e32 v98, v81
	v_fma_f32 v81, v87, s26, -v187
	v_add_f32_e32 v80, v184, v80
	v_exp_f32_e32 v99, v81
	v_fma_f32 v81, v88, s26, -v187
	v_add_f32_e32 v80, v96, v80
	v_exp_f32_e32 v100, v81
	v_fma_f32 v81, v89, s26, -v187
	v_add_f32_e32 v80, v97, v80
	v_exp_f32_e32 v101, v81
	v_fma_f32 v81, v90, s26, -v187
	v_add_f32_e32 v80, v98, v80
	v_exp_f32_e32 v102, v81
	v_fma_f32 v81, v91, s26, -v187
	v_add_f32_e32 v80, v99, v80
	v_exp_f32_e32 v103, v81
	v_fma_f32 v81, v92, s26, -v187
	v_add_f32_e32 v80, v100, v80
	v_exp_f32_e32 v88, v81
	v_fma_f32 v81, v93, s26, -v187
	v_add_f32_e32 v80, v101, v80
	v_exp_f32_e32 v89, v81
	v_fma_f32 v81, v94, s26, -v187
	v_add_f32_e32 v80, v102, v80
	v_exp_f32_e32 v90, v81
	v_fma_f32 v81, v95, s26, -v187
	v_add_f32_e32 v80, v103, v80
	v_exp_f32_e32 v91, v81
	v_fma_f32 v81, v185, s26, -v187
	v_add_f32_e32 v80, v88, v80
	v_exp_f32_e32 v92, v81
	v_fma_f32 v81, v188, s26, -v187
	v_add_f32_e32 v80, v89, v80
	v_exp_f32_e32 v93, v81
	v_fma_f32 v81, v189, s26, -v187
	v_add_f32_e32 v80, v90, v80
	v_exp_f32_e32 v94, v81
	v_fma_f32 v81, v190, s26, -v187
	v_add_f32_e32 v80, v91, v80
	v_exp_f32_e32 v95, v81
	v_add_f32_e32 v80, v92, v80
	v_add_f32_e32 v80, v93, v80
	v_add_f32_e32 v80, v94, v80
	v_fma_f32 v68, v68, s26, -v187
	v_add_f32_e32 v81, v95, v80
	v_exp_f32_e32 v80, v68
	v_fma_f32 v69, v69, s26, -v187
	v_add_f32_e32 v68, v80, v81
	v_exp_f32_e32 v81, v69
	v_fma_f32 v69, v70, s26, -v187
	v_exp_f32_e32 v82, v69
	v_fma_f32 v69, v71, s26, -v187
	v_exp_f32_e32 v83, v69
	v_fma_f32 v69, v72, s26, -v187
	v_exp_f32_e32 v84, v69
	v_fma_f32 v69, v73, s26, -v187
	v_add_f32_e32 v68, v81, v68
	v_exp_f32_e32 v85, v69
	v_fma_f32 v69, v74, s26, -v187
	v_add_f32_e32 v68, v82, v68
	v_exp_f32_e32 v86, v69
	v_fma_f32 v69, v75, s26, -v187
	v_add_f32_e32 v68, v83, v68
	v_exp_f32_e32 v87, v69
	v_fma_f32 v69, v76, s26, -v187
	v_add_f32_e32 v68, v84, v68
	v_exp_f32_e32 v69, v69
	v_fma_f32 v70, v77, s26, -v187
	v_add_f32_e32 v68, v85, v68
	v_exp_f32_e32 v70, v70
	v_fma_f32 v71, v78, s26, -v187
	v_add_f32_e32 v68, v86, v68
	v_exp_f32_e32 v71, v71
	v_fma_f32 v72, v79, s26, -v187
	v_add_f32_e32 v68, v87, v68
	v_exp_f32_e32 v72, v72
	v_fma_f32 v73, v191, s26, -v187
	v_add_f32_e32 v68, v69, v68
	v_exp_f32_e32 v73, v73
	v_fma_f32 v74, v199, s26, -v187
	v_add_f32_e32 v68, v70, v68
	v_exp_f32_e32 v74, v74
	v_sub_f32_e32 v75, v186, v187
	v_add_f32_e32 v68, v71, v68
	v_exp_f32_e32 v75, v75
	v_fma_f32 v76, v200, s26, -v187
	v_add_f32_e32 v68, v72, v68
	v_exp_f32_e32 v76, v76
	v_add_f32_e32 v68, v73, v68
	v_add_f32_e32 v68, v74, v68
	v_add_f32_e32 v68, v75, v68
	v_add_f32_e32 v68, v76, v68
	ds_bpermute_b32 v77, v135, v68
	s_waitcnt lgkmcnt(0)
	v_add_f32_e32 v68, v68, v77
	ds_bpermute_b32 v77, v148, v68
	s_waitcnt lgkmcnt(0)
	v_add_f32_e32 v68, v68, v77
	v_sub_f32_e32 v77, v112, v187
	v_exp_f32_e32 v77, v77
	ds_read_b64_tr_b16 v[186:187], v156 offset:36864
	ds_read_b64_tr_b16 v[200:201], v156 offset:36896
	ds_read_b64_tr_b16 v[188:189], v156 offset:39168
	ds_read_b64_tr_b16 v[202:203], v156 offset:39200
	ds_read_b64_tr_b16 v[208:209], v156 offset:36928
	ds_read_b64_tr_b16 v[210:211], v156 offset:39232
	ds_read_b64_tr_b16 v[212:213], v156 offset:36960
	ds_read_b64_tr_b16 v[214:215], v156 offset:39264
	v_cvt_pk_bf16_f32 v176, v176, v177
	v_cvt_pk_bf16_f32 v177, v178, v179
	v_add_f32_e32 v68, v77, v68
	v_div_scale_f32 v77, s[36:37], v68, v68, 1.0
	v_rcp_f32_e32 v78, v77
	v_cvt_pk_bf16_f32 v178, v180, v181
	v_cvt_pk_bf16_f32 v179, v182, v183
	v_cvt_pk_bf16_f32 v180, v1, v1
	v_cvt_pk_bf16_f32 v181, v1, v1
	v_cvt_pk_bf16_f32 v182, v116, v117
	s_nop 0
	v_fma_f32 v79, -v77, v78, 1.0
	v_fmac_f32_e32 v78, v79, v78
	v_div_scale_f32 v79, vcc, 1.0, v68, 1.0
	v_mul_f32_e32 v112, v79, v78
	v_fma_f32 v185, -v77, v112, v79
	v_cvt_pk_bf16_f32 v183, v144, v184
	s_waitcnt lgkmcnt(5)
	v_mfma_f32_16x16x32_bf16 v[216:219], v[186:189], v[176:179], 0
	v_fmac_f32_e32 v112, v185, v78
	v_fma_f32 v77, -v77, v112, v79
	v_div_fmas_f32 v77, v77, v78, v112
	v_mfma_f32_16x16x32_bf16 v[184:187], v[186:189], v[180:183], 0
	v_div_fixup_f32 v68, v77, v68, 1.0
	s_mov_b64 s[36:37], 0x18000
	s_andn2_b64 vcc, exec, s[64:65]
	s_waitcnt lgkmcnt(4)
	v_mfma_f32_16x16x32_bf16 v[188:191], v[200:203], v[176:179], 0
	v_mfma_f32_16x16x32_bf16 v[200:203], v[200:203], v[180:183], 0
	s_waitcnt lgkmcnt(2)
	v_mfma_f32_16x16x32_bf16 v[220:223], v[208:211], v[176:179], 0
	v_mfma_f32_16x16x32_bf16 v[208:211], v[208:211], v[180:183], 0
	s_waitcnt lgkmcnt(0)
	v_mfma_f32_16x16x32_bf16 v[176:179], v[212:215], v[176:179], 0
	v_mfma_f32_16x16x32_bf16 v[180:183], v[212:215], v[180:183], 0
	ds_read_b64_tr_b16 v[212:213], v156 offset:41472
	ds_read_b64_tr_b16 v[224:225], v156 offset:41504
	ds_read_b64_tr_b16 v[214:215], v156 offset:43776
	ds_read_b64_tr_b16 v[226:227], v156 offset:43808
	ds_read_b64_tr_b16 v[228:229], v156 offset:41536
	ds_read_b64_tr_b16 v[230:231], v156 offset:43840
	ds_read_b64_tr_b16 v[232:233], v156 offset:41568
	ds_read_b64_tr_b16 v[234:235], v156 offset:43872
	v_cvt_pk_bf16_f32 v236, v147, v157
	v_cvt_pk_bf16_f32 v237, v158, v159
	v_cvt_pk_bf16_f32 v238, v160, v161
	v_cvt_pk_bf16_f32 v239, v174, v175
	v_cvt_pk_bf16_f32 v96, v96, v97
	v_cvt_pk_bf16_f32 v97, v98, v99
	v_cvt_pk_bf16_f32 v98, v100, v101
	v_cvt_pk_bf16_f32 v99, v102, v103
	s_waitcnt lgkmcnt(5)
; __device__ __forceinline__ unsigned pk2(float lo, float hi) { return pg8::cvt_pk_bf16(lo, hi); }
; #define ATT_LDV(s) do { _Pragma("unroll") for (int dt = 0; dt < 4; ++dt) { vlo[s][dt] = lds_tr_a(vp0 + (s) * 32 * 72 + 16 * dt); vhi[s][dt] = lds_tr_a(vp0 + (s) * 32 * 72 + 16 * 72 + 16 * dt); } } while (0)
; __device__ __forceinline__ void attn_phase(LAS unsigned char* lds, const bf16* PROJ, bf16* CONCAT, const float* sinks) {
;     ...
;             v2u vlo[5][4], vhi[5][4];
;     ...
; #pragma unroll
;             for (int s2 = 0; s2 < 5; ++s2) {
;                 ATT_LDV(s2);
;                 bf16x8 pf[2];
; #pragma unroll
;                 for (int x = 0; x < 2; ++x) { v4u pw; pw.x = pk2(st[x][2 * s2][0], st[x][2 * s2][1]); pw.y = pk2(st[x][2 * s2][2], st[x][2 * s2][3]);
;                     pw.z = pk2(st[x][2 * s2 + 1][0], st[x][2 * s2 + 1][1]); pw.w = pk2(st[x][2 * s2 + 1][2], st[x][2 * s2 + 1][3]); pf[x] = __builtin_bit_cast(bf16x8, pw); }
; #pragma unroll
;                 for (int dt = 0; dt < 4; ++dt) {
;                     const bf16x8 vf = __builtin_bit_cast(bf16x8, (v4u){vlo[s2][dt].x, vlo[s2][dt].y, vhi[s2][dt].x, vhi[s2][dt].y});
; #pragma unroll
;                     for (int x = 0; x < 2; ++x) ot[x][dt] = __builtin_amdgcn_mfma_f32_16x16x32_bf16(vf, pf[x], ot[x][dt], 0, 0, 0);
;                 }
;             }
	v_mfma_f32_16x16x32_bf16 v[100:103], v[212:215], v[236:239], v[216:219]
	v_mfma_f32_16x16x32_bf16 v[158:161], v[212:215], v[96:99], v[184:187]
	s_waitcnt lgkmcnt(4)
	v_mfma_f32_16x16x32_bf16 v[184:187], v[224:227], v[236:239], v[188:191]
	v_mfma_f32_16x16x32_bf16 v[188:191], v[224:227], v[96:99], v[200:203]
	s_waitcnt lgkmcnt(2)
	v_mfma_f32_16x16x32_bf16 v[200:203], v[228:231], v[236:239], v[220:223]
	v_mfma_f32_16x16x32_bf16 v[208:211], v[228:231], v[96:99], v[208:211]
	s_waitcnt lgkmcnt(0)
	v_mfma_f32_16x16x32_bf16 v[174:177], v[232:235], v[236:239], v[176:179]
	v_mfma_f32_16x16x32_bf16 v[96:99], v[232:235], v[96:99], v[180:183]
	s_nop 1
	ds_read_b64_tr_b16 v[178:179], v156 offset:46080
	ds_read_b64_tr_b16 v[212:213], v156 offset:46112
	ds_read_b64_tr_b16 v[180:181], v156 offset:48384
	ds_read_b64_tr_b16 v[214:215], v156 offset:48416
	ds_read_b64_tr_b16 v[216:217], v156 offset:46144
	ds_read_b64_tr_b16 v[218:219], v156 offset:48448
	ds_read_b64_tr_b16 v[220:221], v156 offset:46176
	ds_read_b64_tr_b16 v[222:223], v156 offset:48480
	v_cvt_pk_bf16_f32 v122, v122, v123
	v_cvt_pk_bf16_f32 v123, v124, v125
	v_cvt_pk_bf16_f32 v124, v126, v127
	v_cvt_pk_bf16_f32 v125, v145, v146
	v_cvt_pk_bf16_f32 v88, v88, v89
	v_cvt_pk_bf16_f32 v89, v90, v91
	v_cvt_pk_bf16_f32 v90, v92, v93
	v_cvt_pk_bf16_f32 v91, v94, v95
	s_waitcnt lgkmcnt(5)
	v_mfma_f32_16x16x32_bf16 v[92:95], v[178:181], v[122:125], v[100:103]
	v_mfma_f32_16x16x32_bf16 v[100:103], v[178:181], v[88:91], v[158:161]
	s_waitcnt lgkmcnt(4)
	v_mfma_f32_16x16x32_bf16 v[144:147], v[212:215], v[122:125], v[184:187]
	v_mfma_f32_16x16x32_bf16 v[158:161], v[212:215], v[88:91], v[188:191]
	s_waitcnt lgkmcnt(2)
	v_mfma_f32_16x16x32_bf16 v[178:181], v[216:219], v[122:125], v[200:203]
	v_mfma_f32_16x16x32_bf16 v[182:185], v[216:219], v[88:91], v[208:211]
	s_waitcnt lgkmcnt(0)
	v_mfma_f32_16x16x32_bf16 v[122:125], v[220:223], v[122:125], v[174:177]
	v_mfma_f32_16x16x32_bf16 v[88:91], v[220:223], v[88:91], v[96:99]
	s_nop 2
	ds_read_b64_tr_b16 v[96:97], v156 offset:50688
	ds_read_b64_tr_b16 v[174:175], v156 offset:50720
	ds_read_b64_tr_b16 v[98:99], v156 offset:52992
	ds_read_b64_tr_b16 v[176:177], v156 offset:53024
	ds_read_b64_tr_b16 v[186:187], v156 offset:50752
	ds_read_b64_tr_b16 v[188:189], v156 offset:53056
	ds_read_b64_tr_b16 v[200:201], v156 offset:50784
	ds_read_b64_tr_b16 v[202:203], v156 offset:53088
	v_cvt_pk_bf16_f32 v116, v113, v109
	v_cvt_pk_bf16_f32 v117, v110, v111
	v_cvt_pk_bf16_f32 v118, v118, v119
	v_cvt_pk_bf16_f32 v119, v120, v121
	v_cvt_pk_bf16_f32 v78, v80, v81
	v_cvt_pk_bf16_f32 v79, v82, v83
	v_cvt_pk_bf16_f32 v80, v84, v85
	v_cvt_pk_bf16_f32 v81, v86, v87
	s_waitcnt lgkmcnt(5)
	v_mfma_f32_16x16x32_bf16 v[82:85], v[96:99], v[116:119], v[92:95]
	v_mfma_f32_16x16x32_bf16 v[92:95], v[96:99], v[78:81], v[100:103]
	s_waitcnt lgkmcnt(4)
	v_mfma_f32_16x16x32_bf16 v[96:99], v[174:177], v[116:119], v[144:147]
	v_mfma_f32_16x16x32_bf16 v[100:103], v[174:177], v[78:81], v[158:161]
	s_waitcnt lgkmcnt(2)
	v_mfma_f32_16x16x32_bf16 v[110:113], v[186:189], v[116:119], v[178:181]
	v_mfma_f32_16x16x32_bf16 v[144:147], v[186:189], v[78:81], v[182:185]
	s_waitcnt lgkmcnt(0)
	v_mfma_f32_16x16x32_bf16 v[116:119], v[200:203], v[116:119], v[122:125]
	v_mfma_f32_16x16x32_bf16 v[78:81], v[200:203], v[78:81], v[88:91]
	ds_read_b64_tr_b16 v[86:87], v156 offset:55296
	ds_read_b64_tr_b16 v[120:121], v156 offset:55328
	s_nop 0
	ds_read_b64_tr_b16 v[88:89], v156 offset:57600
	ds_read_b64_tr_b16 v[122:123], v156 offset:57632
	ds_read_b64_tr_b16 v[124:125], v156 offset:55360
	ds_read_b64_tr_b16 v[126:127], v156 offset:57664
	ds_read_b64_tr_b16 v[158:159], v156 offset:55392
	ds_read_b64_tr_b16 v[160:161], v156 offset:57696
	v_cvt_pk_bf16_f32 v106, v105, v106
	v_cvt_pk_bf16_f32 v107, v107, v108
	v_cvt_pk_bf16_f32 v108, v1, v1
	v_cvt_pk_bf16_f32 v109, v1, v1
	v_cvt_pk_bf16_f32 v70, v69, v70
	v_cvt_pk_bf16_f32 v71, v71, v72
	v_cvt_pk_bf16_f32 v72, v73, v74
	v_cvt_pk_bf16_f32 v73, v75, v76
	s_waitcnt lgkmcnt(5)
; #define LAS __attribute__((address_space(3)))
; #define LAS __attribute__((address_space(3)))
; __device__ __forceinline__ unsigned pk2(float lo, float hi) { return pg8::cvt_pk_bf16(lo, hi); }
; __device__ __forceinline__ void attn_phase(LAS unsigned char* lds, const bf16* PROJ, bf16* CONCAT, const float* sinks) {
;     ...
; #pragma unroll
;                 for (int dt = 0; dt < 4; ++dt) {
;                     const bf16x8 vf = __builtin_bit_cast(bf16x8, (v4u){vlo[s2][dt].x, vlo[s2][dt].y, vhi[s2][dt].x, vhi[s2][dt].y});
; #pragma unroll
;                     for (int x = 0; x < 2; ++x) ot[x][dt] = __builtin_amdgcn_mfma_f32_16x16x32_bf16(vf, pf[x], ot[x][dt], 0, 0, 0);
;                 }
;             }
;     ...
; #pragma unroll
;             for (int x = 0; x < 2; ++x) {
;                 LAS bf16* stg = (LAS bf16*)(lds + 73728) + (wave * 2 + x) * (16 * 72);
; #pragma unroll
;                 for (int dt = 0; dt < 4; ++dt) *(LAS v2u*)(stg + fr * 72 + 16 * dt + 4 * fq) = (v2u){pk2(ot[x][dt][0] * inv[x], ot[x][dt][1] * inv[x]), pk2(ot[x][dt][2] * inv[x], ot[x][dt][3] * inv[x])};
;                 bf16* op = CONCAT + (qrow0 - fr + 16 * (2 * p + x)) * DM + h * 64;
; #pragma unroll
;                 for (int i = 0; i < 2; ++i) { const int row = 8 * i + (lane >> 3), chn = lane & 7;
;                     *(v4u*)(op + (size_t)row * DM + chn * 8) = *(const LAS v4u*)(stg + row * 72 + chn * 8); }
;             }
;         }
;         if (ul + (int)gridDim.x < NB * 64 * 2) ATT_LOAD_Q(ATT_UNIT(ul + (int)gridDim.x));
;         __syncthreads();
;     }
	v_mfma_f32_16x16x32_bf16 v[74:77], v[86:89], v[106:109], v[82:85]
	v_mfma_f32_16x16x32_bf16 v[82:85], v[86:89], v[70:73], v[92:95]
	s_waitcnt lgkmcnt(4)
	v_mfma_f32_16x16x32_bf16 v[86:89], v[120:123], v[106:109], v[96:99]
	s_nop 4
	v_mul_f32_e32 v69, v104, v74
	v_mul_f32_e32 v74, v104, v75
	v_mul_f32_e32 v75, v104, v77
	s_waitcnt lgkmcnt(2)
	v_mfma_f32_16x16x32_bf16 v[94:97], v[124:127], v[106:109], v[110:113]
	v_cvt_pk_bf16_f32 v74, v69, v74
	v_mul_f32_e32 v69, v104, v76
	v_cvt_pk_bf16_f32 v75, v69, v75
	s_waitcnt lgkmcnt(0)
	v_mfma_f32_16x16x32_bf16 v[106:109], v[158:161], v[106:109], v[116:119]
	ds_write_b64 v150, v[74:75]
	v_mul_f32_e32 v69, v104, v86
	v_mul_f32_e32 v74, v104, v87
	v_mul_f32_e32 v75, v104, v89
	v_cvt_pk_bf16_f32 v74, v69, v74
	v_mul_f32_e32 v69, v104, v88
	v_cvt_pk_bf16_f32 v75, v69, v75
	ds_write_b64 v150, v[74:75] offset:32
	v_mul_f32_e32 v69, v104, v94
	v_mul_f32_e32 v74, v104, v95
	v_mul_f32_e32 v75, v104, v97
	v_cvt_pk_bf16_f32 v74, v69, v74
	v_mul_f32_e32 v69, v104, v96
	v_cvt_pk_bf16_f32 v75, v69, v75
	ds_write_b64 v150, v[74:75] offset:64
	v_mul_f32_e32 v69, v104, v106
	v_mul_f32_e32 v74, v104, v107
	v_mul_f32_e32 v75, v104, v109
	v_cvt_pk_bf16_f32 v74, v69, v74
	v_mul_f32_e32 v69, v104, v108
	v_cvt_pk_bf16_f32 v75, v69, v75
	ds_write_b64 v150, v[74:75] offset:96
	ds_read_b128 v[74:77], v153
	v_mfma_f32_16x16x32_bf16 v[90:93], v[120:123], v[70:73], v[100:103]
	v_mul_f32_e32 v69, v68, v82
	v_mfma_f32_16x16x32_bf16 v[98:101], v[124:127], v[70:73], v[144:147]
	v_mfma_f32_16x16x32_bf16 v[70:73], v[158:161], v[70:73], v[78:81]
	s_nop 2
	v_lshl_add_u64 v[78:79], v[114:115], 0, s[34:35]
	v_lshl_add_u64 v[80:81], v[78:79], 0, v[0:1]
	s_waitcnt lgkmcnt(0)
	global_store_dwordx4 v[80:81], v[74:77], off
	ds_read_b128 v[74:77], v154
	v_lshl_add_u64 v[78:79], v[78:79], 0, v[142:143]
	s_waitcnt lgkmcnt(0)
	global_store_dwordx4 v[78:79], v[74:77], off
	s_nop 1
	v_mul_f32_e32 v74, v68, v83
	v_cvt_pk_bf16_f32 v74, v69, v74
	v_mul_f32_e32 v69, v68, v84
	v_mul_f32_e32 v75, v68, v85
	v_cvt_pk_bf16_f32 v75, v69, v75
	ds_write_b64 v150, v[74:75] offset:2304
	v_mul_f32_e32 v69, v68, v90
	v_mul_f32_e32 v74, v68, v91
	v_cvt_pk_bf16_f32 v74, v69, v74
	v_mul_f32_e32 v69, v68, v92
	v_mul_f32_e32 v75, v68, v93
	v_cvt_pk_bf16_f32 v75, v69, v75
	ds_write_b64 v150, v[74:75] offset:2336
	v_mul_f32_e32 v69, v68, v98
	v_mul_f32_e32 v74, v68, v99
	v_cvt_pk_bf16_f32 v74, v69, v74
	v_mul_f32_e32 v69, v68, v100
	v_mul_f32_e32 v75, v68, v101
	v_cvt_pk_bf16_f32 v75, v69, v75
	v_mul_f32_e32 v69, v68, v70
	v_mul_f32_e32 v70, v68, v71
	ds_write_b64 v150, v[74:75] offset:2368
	v_cvt_pk_bf16_f32 v70, v69, v70
	v_mul_f32_e32 v69, v68, v72
	v_mul_f32_e32 v68, v68, v73
	v_cvt_pk_bf16_f32 v71, v69, v68
	ds_write_b64 v150, v[70:71] offset:2400
	ds_read_b128 v[68:71], v153 offset:2304
	v_lshl_add_u64 v[72:73], v[114:115], 0, s[36:37]
	v_lshl_add_u64 v[74:75], v[72:73], 0, v[0:1]
	v_lshl_add_u64 v[72:73], v[72:73], 0, v[142:143]
	s_waitcnt lgkmcnt(0)
	global_store_dwordx4 v[74:75], v[68:71], off
	ds_read_b128 v[68:71], v154 offset:2304
	s_waitcnt lgkmcnt(0)
	global_store_dwordx4 v[72:73], v[68:71], off
	s_cbranch_vccnz .LBB0_268
	s_branch .LBB0_268
